# workspace pointer read back from spare VGPR lanes at 51 sites (incl. the two per-tile P7 sites) instead of kernarg SMEM reloads
# speedup vs baseline: 1.0229x; 1.0017x over previous
; #define LAS __attribute__((address_space(3)))
; DI unsigned xb_add(unsigned* p, unsigned v) { return __hip_atomic_fetch_add(p, v, __ATOMIC_RELAXED, __HIP_MEMORY_SCOPE_AGENT); }
; DI unsigned xb_xcc_id() { return (unsigned)__builtin_amdgcn_s_getreg((3 << 11) | 20) & 0xFu; }
; #define G_WS (wsp())
; DI XcdBarrier xcd_barrier_post(unsigned* bar, volatile LAS unsigned* st) {
;   XcdBarrier b; b.bar = bar; b.x = xb_xcc_id(); b.st = st;
;   if (threadIdx.x == 0) (void)xb_add(&bar[XB_XCNT(b.x)], 1u);
;   return b;
; __global__ void __launch_bounds__(512, 2) mega(Params p) {
;     ...
;   volatile LAS unsigned* xst = (volatile LAS unsigned*)(smem + SMEM_MAIN);
;   if (t < 4) xst[t] = 0u;
;   __syncthreads();
;   const XcdBarrier xbar = xcd_barrier_post((unsigned*)(G_WS + OFF_BAR), xst);
.LBB0_3:
	s_or_b64 exec, exec, s[0:1]
	s_mov_b32 s0, 25
	s_waitcnt lgkmcnt(0)
	s_barrier
	s_ashr_i32 s1, s0, 31
	s_lshl_b64 s[0:1], s[0:1], 3
	s_add_u32 s0, s70, s0
	s_addc_u32 s1, s71, s1
	v_readlane_b32 s2, v255, 60
	v_readlane_b32 s3, v255, 61
	s_nop 4
	s_getreg_b32 s0, hwreg(HW_REG_XCC_ID, 0, 4)
	s_mov_b32 s4, 25
	s_mov_b32 s6, 0
	v_cmp_eq_u32_e64 s[8:9], 0, v224
	s_waitcnt lgkmcnt(0)
	s_add_u32 s10, s2, 0xf8e2000
	s_addc_u32 s11, s3, 0
	s_and_b32 s40, s0, 15
	v_writelane_b32 v255, s40, 59
	s_mov_b32 s100, 2
	s_nop 0
	v_writelane_b32 v255, s100, 56
	s_mov_b64 s[0:1], exec
	v_writelane_b32 v252, s8, 3
	s_nop 1
	v_writelane_b32 v252, s9, 4
	s_and_b64 s[8:9], s[0:1], s[8:9]
	s_mov_b64 exec, s[8:9]
	s_cbranch_execz .LBB0_6
	s_mov_b64 s[8:9], exec
	v_mbcnt_lo_u32_b32 v0, s8, 0
	v_mbcnt_hi_u32_b32 v0, s9, v0
	v_cmp_eq_u32_e32 vcc, 0, v0
	s_and_b64 s[12:13], exec, vcc
	s_mov_b64 exec, s[12:13]
	s_cbranch_execz .LBB0_6
	s_lshl_b32 s5, s40, 8
	s_bcnt1_i32_b64 s7, s[8:9]
	v_mov_b32_e32 v0, s5
	v_mov_b32_e32 v1, s7
	global_atomic_add v0, v1, s[10:11] offset:1024
	v_readlane_b32 s100, v252, 0
	s_lshl_b32 s101, s40, 2
	s_and_b32 s100, s100, 63
	s_lshl_b32 s101, 1, s101
	s_lshl_b32 s100, s100, 2
	s_cmp_gt_u32 s40, 7
	s_cselect_b32 s101, 0, s101
	v_mov_b32_e32 v0, s100
	v_mov_b32_e32 v1, s101
	s_nop 0
	global_atomic_add v0, v1, s[10:11]

; DI int tid_opaque() { int t = threadIdx.x; asm volatile("" : "+v"(t)); return t; }
; DI double dpow(double c, int n) { double r = 1.0; for (int i = 0; i < n; ++i) r *= c; return r; }
; #define G_CS1 ((float2*)(wsp() + OFF_CS1))
; DI float2 cossin(double ang) {
;   double rev = ang * 0.15915494309189535;
;   rev -= rint(rev);
;   const float f = (float)rev;
;   float2 o;
;   o.x = __builtin_amdgcn_cosf(f);
;   o.y = __builtin_amdgcn_sinf(f);
;   return o;
; __global__ void __launch_bounds__(512, 2) mega(Params p) {
;     ...
;   for (int idx = bid * NT + tid_opaque(); idx < 163840; idx += nb * NT) {
;     if (idx < 65536) {
;       const int pos = idx >> 5, i = idx & 31;
;       G_CS1[idx] = cossin((double)pos * dpow(0.7498942093324559, i));
.LBB0_18:
	s_or_b64 exec, exec, s[30:31]
	s_mov_b32 s30, 25
	s_ashr_i32 s31, s30, 31
	v_ashrrev_i32_e32 v1, 5, v0
	s_lshl_b64 s[30:31], s[30:31], 3
	v_cvt_f64_i32_e32 v[10:11], v1
	s_add_u32 s30, s70, s30
	v_mul_f64 v[4:5], v[4:5], v[10:11]
	s_addc_u32 s31, s71, s31
	v_mul_f64 v[10:11], v[4:5], s[18:19]
	v_readlane_b32 s30, v255, 60
	v_readlane_b32 s31, v255, 61
	s_nop 4
	v_rndne_f64_e32 v[10:11], v[10:11]
	v_fma_f64 v[4:5], v[4:5], s[18:19], -v[10:11]
	v_cvt_f32_f64_e32 v1, v[4:5]
	v_cos_f32_e32 v2, v1
	v_sin_f32_e32 v9, v1
	v_ashrrev_i32_e32 v1, 31, v0
	s_waitcnt lgkmcnt(0)
	v_lshl_add_u64 v[10:11], v[0:1], 3, s[30:31]
	v_lshl_add_u64 v[4:5], v[10:11], 0, s[26:27]
	v_add_co_u32_e32 v10, vcc, 0xf7a2000, v10
	s_nop 1
	v_addc_co_u32_e32 v11, vcc, 0, v11, vcc
	global_store_dword v[10:11], v2, off

; DI double dpow(double c, int n) { double r = 1.0; for (int i = 0; i < n; ++i) r *= c; return r; }
; #define G_CSC ((float2*)(wsp() + OFF_CSC))
; DI float2 cossin(double ang) {
;   double rev = ang * 0.15915494309189535;
;   rev -= rint(rev);
;   const float f = (float)rev;
;   float2 o;
;   o.x = __builtin_amdgcn_cosf(f);
;   o.y = __builtin_amdgcn_sinf(f);
;   return o;
; __global__ void __launch_bounds__(512, 2) mega(Params p) {
;     ...
;     } else {
;       const int e = idx - 131072;
;       const int pos = e >> 4, i = e & 15;
;       G_CSC[e] = cossin((double)pos * dpow(0.5623413251903491, i));
.LBB0_26:
	s_or_b64 exec, exec, s[34:35]
	s_mov_b32 s34, 25
	v_add_u32_e32 v2, 0xfffe0000, v0
	s_ashr_i32 s35, s34, 31
	v_lshrrev_b32_e32 v1, 4, v2
	s_lshl_b64 s[34:35], s[34:35], 3
	v_cvt_f64_u32_e32 v[10:11], v1
	s_add_u32 s34, s70, s34
	v_mul_f64 v[4:5], v[4:5], v[10:11]
	s_addc_u32 s35, s71, s35
	v_mul_f64 v[10:11], v[4:5], s[18:19]
	v_readlane_b32 s34, v255, 60
	v_readlane_b32 s35, v255, 61
	s_nop 4
	v_rndne_f64_e32 v[10:11], v[10:11]
	v_fma_f64 v[4:5], v[4:5], s[18:19], -v[10:11]
	v_cvt_f32_f64_e32 v1, v[4:5]
	v_cos_f32_e32 v12, v1
	s_waitcnt lgkmcnt(0)
	v_lshl_add_u64 v[10:11], v[2:3], 3, s[34:35]
	v_lshl_add_u64 v[4:5], v[10:11], 0, s[20:21]
	v_add_co_u32_e32 v10, vcc, 0xf8a2000, v10
	v_sin_f32_e32 v9, v1
	s_nop 0
	v_addc_co_u32_e32 v11, vcc, 0, v11, vcc
	global_store_dword v[10:11], v12, off

; DI double dpow(double c, int n) { double r = 1.0; for (int i = 0; i < n; ++i) r *= c; return r; }
; #define G_CS2 ((float2*)(wsp() + OFF_CS2))
; DI float2 cossin(double ang) {
;   double rev = ang * 0.15915494309189535;
;   rev -= rint(rev);
;   const float f = (float)rev;
;   float2 o;
;   o.x = __builtin_amdgcn_cosf(f);
;   o.y = __builtin_amdgcn_sinf(f);
;   return o;
; __global__ void __launch_bounds__(512, 2) mega(Params p) {
;     ...
;     } else if (idx < 131072) {
;       const int e = idx - 65536;
;       const int pos = e >> 5, i = e & 31;
;       const double a = (i < 16) ? (double)(pos >> 6) * dpow(0.5623413251903491, i) : (double)(pos & 63) * dpow(0.5623413251903491, i - 16);
;       G_CS2[e] = cossin(a);
.LBB0_40:
	s_or_b64 exec, exec, s[34:35]
	s_mov_b32 s34, 25
	s_ashr_i32 s35, s34, 31
	s_lshl_b64 s[34:35], s[34:35], 3
	s_add_u32 s34, s70, s34
	s_addc_u32 s35, s71, s35
	v_mul_f64 v[10:11], v[4:5], s[18:19]
	v_readlane_b32 s34, v255, 60
	v_readlane_b32 s35, v255, 61
	s_nop 4
	v_rndne_f64_e32 v[10:11], v[10:11]
	v_fma_f64 v[4:5], v[4:5], s[18:19], -v[10:11]
	v_cvt_f32_f64_e32 v1, v[4:5]
	v_cos_f32_e32 v12, v1
	v_sin_f32_e32 v9, v1
	s_waitcnt lgkmcnt(0)
	v_lshl_add_u64 v[10:11], v[2:3], 3, s[34:35]
	v_lshl_add_u64 v[4:5], v[10:11], 0, s[22:23]
	v_add_co_u32_e32 v10, vcc, 0xf822000, v10
	s_nop 1
	v_addc_co_u32_e32 v11, vcc, 0, v11, vcc
	global_store_dword v[10:11], v12, off

; DI unsigned char* wsp() { return (unsigned char*)inp(25); }
; DI void convert_mat(const float* W, int K, int N, const float* g, bf16_t* Wt, int mode, int& off, int vb, int nb, bool f16 = false) {
;   const int ntn = (N + 127) >> 7;
;   const int ntiles = (K >> 6) * ntn;
;   const int first = (int)((vb + nb - (off % nb)) % nb);
;   for (int i = first; i < ntiles; i += nb) convert_tile(W, K, N, g, Wt, mode, i / ntn, i % ntn, f16);
;   off += ntiles;
; }
; DI void convert_layer(int L, int vb, int vnb) {
;   bf16_t* wb = (bf16_t*)(wsp() + OFF_W) + (size_t)(L & 1) * WSZ;
;   const int j = L >> 1;
;   int off = 0;
;   if ((L & 1) == 0) {
;     convert_mat(inp(3) + (size_t)j * 1024 * 1536, 1024, 1536, inp(2) + L * 1024, wb + W_IN, 0, off, vb, vnb, true);
.LBB0_47:
	s_or_b64 exec, exec, s[0:1]
	s_mov_b32 s0, 25
	s_load_dwordx2 s[4:5], s[70:71], 0xd0
	s_ashr_i32 s1, s0, 31
	s_lshl_b64 s[0:1], s[0:1], 3
	s_add_u32 s0, s70, s0
	s_addc_u32 s1, s71, s1
	s_waitcnt lgkmcnt(0)
	s_mov_b64 s[6:7], s[4:5]
	s_abs_i32 s12, s6
	v_cvt_f32_u32_e32 v0, s12
	s_sub_i32 s7, 0, s12
	v_readlane_b32 s5, v252, 0
	s_add_i32 s6, s6, s5
	v_rcp_iflag_f32_e32 v0, v0
	s_ashr_i32 s5, s6, 31
	v_writelane_b32 v252, s6, 7
	s_abs_i32 s6, s6
	v_mul_f32_e32 v0, 0x4f7ffffe, v0
	v_cvt_u32_f32_e32 v0, v0
	v_readlane_b32 s0, v255, 60
	v_readlane_b32 s1, v255, 61
	s_nop 4
	s_mov_b32 s8, 3
	s_mov_b32 s4, 2
	v_readfirstlane_b32 s9, v0
	s_mul_i32 s7, s7, s9
	s_mul_hi_u32 s7, s9, s7
	s_add_i32 s7, s9, s7
	v_writelane_b32 v252, s7, 8
	s_mul_hi_u32 s7, s6, s7
	s_mul_i32 s7, s7, s12
	s_sub_i32 s6, s6, s7
	s_sub_i32 s7, s6, s12
	s_cmp_ge_u32 s6, s12
	s_cselect_b32 s6, s7, s6
	s_sub_i32 s7, s6, s12
	s_cmp_ge_u32 s6, s12
	s_cselect_b32 s6, s7, s6
	s_xor_b32 s6, s6, s5
	s_sub_i32 s5, s6, s5
	s_cmpk_lt_i32 s5, 0xc0
	v_writelane_b32 v252, s12, 9
	s_cselect_b64 s[6:7], -1, 0
	v_writelane_b32 v252, s6, 10
	s_cmpk_gt_i32 s5, 0xbf
	s_nop 0
	v_writelane_b32 v252, s7, 11
	v_writelane_b32 v252, s5, 12
	s_cbranch_scc1 .LBB0_60
	s_waitcnt lgkmcnt(0)
	s_add_u32 s6, s0, 0xc000000
	s_addc_u32 s7, s1, 0
	s_ashr_i32 s9, s8, 31
	s_lshl_b64 s[8:9], s[8:9], 3
	s_add_u32 s14, s70, s8
	s_addc_u32 s15, s71, s9
	s_ashr_i32 s5, s4, 31
	s_lshl_b64 s[4:5], s[4:5], 3
	s_add_u32 s4, s70, s4
	s_addc_u32 s5, s71, s5
	s_load_dwordx2 s[8:9], s[4:5], 0x0
	s_load_dwordx2 s[12:13], s[14:15], 0x0
	v_readlane_b32 s25, v252, 12
	s_load_dwordx2 s[4:5], s[70:71], 0xd0
	s_movk_i32 s22, 0x600
	s_waitcnt lgkmcnt(0)
	s_cmp_lg_u64 s[8:9], 0
	s_cselect_b64 s[14:15], -1, 0
	v_cndmask_b32_e64 v0, 0, 1, s[14:15]
	s_lshl_b32 s20, s25, 7
	s_lshl_b32 s21, s4, 7
	s_movk_i32 s23, 0x1800
	s_movk_i32 s24, 0x204
	v_cmp_ne_u32_e64 s[4:5], 1, v0
	v_mov_b32_e32 v17, 0
	s_branch .LBB0_50

; #define G_WS (wsp())
; #define G_SS ((float*)(wsp() + OFF_SS))
; #define G_CS1 ((float2*)(wsp() + OFF_CS1))
; #define G_CS2 ((float2*)(wsp() + OFF_CS2))
; #define G_CSC ((float2*)(wsp() + OFF_CSC))
; __global__ void __launch_bounds__(512, 2) mega(Params p) {
;     ...
;   for (int L = 0; L < 4; ++L) {
;     const int j = L >> 1;
;     const bool odd = (L & 1) != 0;
;     const bf16_t* wb = (const bf16_t*)(G_WS + OFF_W) + (size_t)(L & 1) * WSZ;
;     Ep e{};
;     e.cs1 = G_CS1; e.cs2 = G_CS2; e.csc = G_CSC;
;     {
;       const int nin = (odd ? 8 : 6) * 64;
;       for (int rp = 0; rp < REP_P1; ++rp)
;       for (int item = bid; item < nin; item += nb) {
;         const int nt = item >> 6, mt = item & 63;
;         e.ss = G_SS; e.nss = 16; e.inv_n = 1.f / 1024.f; e.out = G_ZB; e.ldo = ZLD;
.LBB0_184:
	s_lshr_b32 s6, s1, 1
	s_and_b32 s3, s1, 1
	s_cmp_eq_u32 s3, 0
	s_mov_b32 s0, 25
	v_writelane_b32 v254, s1, 41
	s_cselect_b64 s[40:41], -1, 0
	s_ashr_i32 s1, s0, 31
	s_lshl_b64 s[0:1], s[0:1], 3
	s_add_u32 s0, s70, s0
	s_addc_u32 s1, s71, s1
	v_readlane_b32 s4, v255, 60
	v_readlane_b32 s5, v255, 61
	s_nop 4
	s_mul_i32 s0, s3, 0x1b20000
	s_mov_b32 s2, 25
	s_waitcnt lgkmcnt(0)
	s_add_u32 s0, s4, s0
	v_writelane_b32 v254, s4, 42
	s_addc_u32 s1, s5, 0
	s_add_u32 s0, s0, 0xc000000
	v_writelane_b32 v254, s5, 43
	v_writelane_b32 v254, s0, 44
	s_addc_u32 s0, s1, 0
	v_writelane_b32 v254, s0, 45
	s_mov_b32 s0, 25
	s_mov_b32 s4, 25
	s_ashr_i32 s5, s4, 31
	s_lshl_b64 s[4:5], s[4:5], 3
	s_add_u32 s4, s70, s4
	s_addc_u32 s5, s71, s5
	v_readlane_b32 s4, v255, 60
	v_readlane_b32 s5, v255, 61
	s_nop 4
	v_writelane_b32 v254, s8, 46
	s_nop 1
	v_writelane_b32 v254, s9, 47
	v_cndmask_b32_e64 v0, 0, 1, s[8:9]
	s_waitcnt lgkmcnt(0)
	s_add_u32 s8, s4, 0xf8a2000
	s_addc_u32 s9, s5, 0
	s_cmp_eq_u32 s3, 1
	s_cselect_b64 s[38:39], -1, 0
	v_readfirstlane_b32 s1, v0
	s_and_b64 s[4:5], s[38:39], exec
	s_movk_i32 s3, 0x180
	s_cselect_b32 s7, 0x200, s3
	v_readlane_b32 s3, v252, 0
	s_mul_i32 s1, s1, 0x1b20000
	s_cmp_ge_i32 s3, s7
	v_writelane_b32 v254, s1, 48
	s_cbranch_scc1 .LBB0_263
	s_ashr_i32 s3, s2, 31
	s_lshl_b64 s[2:3], s[2:3], 3
	s_add_u32 s2, s70, s2
	s_addc_u32 s3, s71, s3
	s_load_dwordx2 s[2:3], s[2:3], 0x0
	v_readlane_b32 s12, v254, 35
	v_readlane_b32 s4, v254, 48
	v_readlane_b32 s33, v252, 0
	v_readlane_b32 s24, v254, 17
	s_waitcnt lgkmcnt(0)
	s_add_u32 s42, s2, 0xf7a2000
	s_addc_u32 s43, s3, 0
	s_ashr_i32 s1, s0, 31
	s_lshl_b64 s[0:1], s[0:1], 3
	s_add_u32 s0, s70, s0
	s_addc_u32 s1, s71, s1
	s_load_dwordx2 s[0:1], s[0:1], 0x0
	v_readlane_b32 s2, v254, 42
	v_readlane_b32 s3, v254, 43
	s_mov_b32 s25, s33
	v_readlane_b32 s13, v254, 36
	s_waitcnt lgkmcnt(0)
	s_add_u32 s44, s0, 0xf822000
	s_addc_u32 s45, s1, 0
	s_lshl_b32 s0, s6, 6
	s_mov_b32 s1, s12
	s_add_u32 s46, s2, s4
	s_addc_u32 s47, s3, 0
	s_lshl_b64 s[48:49], s[0:1], 2
	v_readlane_b32 s14, v254, 37
	v_readlane_b32 s15, v254, 38
	s_branch .LBB0_188

; #define WAIT_V8(n) asm volatile("s_waitcnt vmcnt(" #n ")" ::: "memory")
; #define BAR8 __builtin_amdgcn_s_barrier()
; #define G_SS ((float*)(wsp() + OFF_SS))
;     ...
;     STAGE8(SB8(0, 0), Bt, K, bcol, 0); STAGE8(SA8(0, 0), A, lda, brow, 0);
;     STAGE8(SB8(0, 1), Bt, K, bcol + 128, 0); STAGE8(SA8(0, 1), A, lda, brow + 128, 0);
;   }
;   if (wr == 1) BAR8;
;   WAIT_V8(4); BAR8;
;   STAGE8(SB8(1, 0), Bt, K, bcol, 1); STAGE8(SA8(1, 0), A, lda, brow, 1); STAGE8(SB8(1, 1), Bt, K, bcol + 128, 1);
; __global__ void __launch_bounds__(512, 2) mega(Params p) {
;     ...
;       for (int item = bid; item < nin; item += nb) {
;         const int nt = item >> 6, mt = item & 63;
;         e.ss = G_SS; e.nss = 16; e.inv_n = 1.f / 1024.f; e.out = G_ZB; e.ldo = ZLD;
;         if (!odd) {
;           e.g_a = inp(4) + j * 64; e.g_b = inp(5) + j * 64;
;           gemm_tile<EPI_IN_AB, 256, true>(G_XB, DM, wb + W_IN, DM, mt * 256, nt * 256, e);
.LBB0_188:
	s_and_b32 s0, s25, 63
	s_lshl_b32 s30, s0, 19
	s_and_b32 s0, s24, 0xffffff00
	s_ashr_i32 s1, s0, 31
	s_lshl_b64 s[56:57], s[0:1], 11
	s_mov_b32 s0, 25
	s_ashr_i32 s1, s0, 31
	s_and_b32 s20, s33, 63
	s_lshl_b64 s[0:1], s[0:1], 3
	s_add_u32 s0, s70, s0
	s_addc_u32 s1, s71, s1
	v_readlane_b32 s0, v255, 60
	v_readlane_b32 s1, v255, 61
	s_nop 4
	v_readlane_b32 s12, v254, 35
	s_mov_b32 s31, s12
	v_readlane_b32 s13, v254, 36
	v_readlane_b32 s14, v254, 37
	s_waitcnt lgkmcnt(0)
	s_add_u32 s54, s0, 0xf640000
	s_mov_b32 s0, 25
	s_addc_u32 s55, s1, 0
	s_ashr_i32 s1, s0, 31
	s_lshl_b64 s[0:1], s[0:1], 3
	s_add_u32 s0, s70, s0
	s_addc_u32 s1, s71, s1
	v_readlane_b32 s0, v255, 60
	v_readlane_b32 s1, v255, 61
	s_nop 4
	v_readlane_b32 s15, v254, 38
	s_waitcnt lgkmcnt(0)
	s_add_u32 s50, s0, 0x2000000
	s_addc_u32 s51, s1, 0
	s_lshl_b32 s0, s33, 2
	s_lshl_b32 s36, s20, 8
	s_and_b32 s52, s0, 0xffffff00
	s_andn2_b64 vcc, exec, s[40:41]
	s_mov_b64 s[0:1], -1
	s_cbranch_vccnz .LBB0_238
	s_mov_b32 s0, 4
	s_ashr_i32 s1, s0, 31
	s_lshl_b64 s[0:1], s[0:1], 3
	s_add_u32 s0, s70, s0
	s_addc_u32 s1, s71, s1
	s_mov_b32 s2, 5
	s_load_dwordx2 s[0:1], s[0:1], 0x0
	s_ashr_i32 s3, s2, 31
	s_lshl_b64 s[2:3], s[2:3], 3
	s_add_u32 s2, s70, s2
	s_addc_u32 s3, s71, s3
	s_mov_b32 s4, 25
	s_load_dwordx2 s[2:3], s[2:3], 0x0
	s_ashr_i32 s5, s4, 31
	s_lshl_b64 s[4:5], s[4:5], 3
	s_add_u32 s4, s70, s4
	s_addc_u32 s5, s71, s5
	v_mov_b32_e32 v3, v224
	v_readlane_b32 s12, v255, 60
	v_readlane_b32 s13, v255, 61
	s_nop 4
	s_ashr_i32 s53, s52, 31
	v_bfe_i32 v1, v3, 27, 1
	s_waitcnt vmcnt(10)
	v_lshlrev_b32_e32 v150, 4, v3
	v_lshrrev_b32_e32 v1, 22, v1
	v_add_u32_e32 v1, v150, v1
	v_and_b32_e32 v1, 0xfffffc00, v1
	v_ashrrev_i32_e32 v0, 31, v3
	v_sub_u32_e32 v1, v150, v1
	v_lshrrev_b32_e32 v0, 26, v0
	v_lshrrev_b32_e32 v5, 4, v1
	v_add_u32_e32 v0, v3, v0
	v_bitop3_b32 v5, v5, v1, 32 bitop3:0x6c
	v_ashrrev_i32_e32 v1, 31, v1
	v_ashrrev_i32_e32 v0, 6, v0
	v_lshrrev_b32_e32 v1, 26, v1
	v_lshlrev_b32_e32 v6, 3, v0
	v_add_u32_e32 v1, v5, v1
	v_and_b32_e32 v6, -16, v6
	v_ashrrev_i32_e32 v1, 6, v1
	v_add_u32_e32 v6, v1, v6
	v_mul_i32_i24_e32 v1, 64, v1
	v_lshlrev_b32_e32 v0, 5, v0
	v_sub_u32_e32 v1, v5, v1
	v_mov_b32_e32 v14, 1
	s_waitcnt vmcnt(9)
	v_add_u32_e32 v155, 0x2000, v150
	s_lshl_b64 s[4:5], s[52:53], 11
	v_readlane_b32 s21, v254, 44
	v_and_b32_e32 v0, 32, v0
	v_ashrrev_i16_sdwa v1, v14, sext(v1) dst_sel:DWORD dst_unused:UNUSED_PAD src0_sel:DWORD src1_sel:BYTE_0
	v_ashrrev_i32_e32 v5, 31, v155
	s_add_u32 s4, s21, s4
	v_readlane_b32 s27, v254, 45
	v_add_u32_sdwa v0, v0, sext(v1) dst_sel:DWORD dst_unused:UNUSED_PAD src0_sel:DWORD src1_sel:WORD_0
	v_ashrrev_i32_e32 v7, 31, v6
	v_lshrrev_b32_e32 v5, 22, v5
	s_addc_u32 s5, s27, s5
	v_lshlrev_b64 v[132:133], 11, v[6:7]
	v_ashrrev_i32_e32 v1, 31, v0
	v_add_u32_e32 v5, v155, v5
	v_lshl_add_u64 v[8:9], s[4:5], 0, v[132:133]
	v_lshlrev_b64 v[6:7], 1, v[0:1]
	v_ashrrev_i32_e32 v5, 10, v5
	v_lshl_add_u64 v[10:11], v[8:9], 0, v[6:7]
	v_mul_i32_i24_e32 v8, 0x400, v5
	v_sub_u32_e32 v8, v155, v8
	v_lshrrev_b32_e32 v9, 4, v8
	v_bitop3_b32 v9, v9, v8, 32 bitop3:0x6c
	v_ashrrev_i32_e32 v12, 31, v9
	v_lshrrev_b32_e32 v12, 26, v12
	v_add_u32_e32 v12, v9, v12
	v_lshlrev_b32_e32 v8, 3, v5
	v_ashrrev_i32_e32 v13, 6, v12
	v_and_b32_e32 v12, 0xc0, v12
	v_and_b32_e32 v8, -16, v8
	v_lshlrev_b32_e32 v5, 5, v5
	v_sub_u32_e32 v9, v9, v12
	v_add_u32_e32 v8, v13, v8
	v_and_b32_e32 v5, 32, v5
	v_ashrrev_i16_sdwa v9, v14, sext(v9) dst_sel:DWORD dst_unused:UNUSED_PAD src0_sel:DWORD src1_sel:BYTE_0
	v_add_u32_e32 v151, 0x10000, v150
	v_add_u32_sdwa v134, v5, sext(v9) dst_sel:DWORD dst_unused:UNUSED_PAD src0_sel:DWORD src1_sel:WORD_0
	v_ashrrev_i32_e32 v9, 31, v8
	v_readfirstlane_b32 s14, v151
	v_lshlrev_b64 v[136:137], 11, v[8:9]
	s_waitcnt vmcnt(8)
	v_add_u32_e32 v157, 0x12000, v150
	v_mov_b32_e32 v4, v2
	s_mov_b32 m0, s14
	v_lshl_add_u64 v[12:13], s[4:5], 0, v[136:137]
	v_readfirstlane_b32 s4, v157
	global_load_lds_dwordx4 v[10:11], off
	s_mov_b32 m0, s4
	s_lshl_b32 s4, s20, 19
	v_ashrrev_i32_e32 v135, 31, v134
	s_waitcnt lgkmcnt(0)
	s_add_u32 s4, s12, s4
	v_lshlrev_b64 v[8:9], 1, v[134:135]
	s_addc_u32 s5, s13, 0
	v_lshl_add_u64 v[12:13], v[12:13], 0, v[8:9]
	v_lshl_add_u64 v[14:15], s[4:5], 0, v[132:133]
	v_readfirstlane_b32 s14, v150
	s_or_b32 s58, s52, 0x80
	global_load_lds_dwordx4 v[12:13], off
	v_lshl_add_u64 v[14:15], v[14:15], 0, v[6:7]
	s_mov_b32 m0, s14
	v_readfirstlane_b32 s14, v155
	s_ashr_i32 s59, s58, 31
	global_load_lds_dwordx4 v[14:15], off
	s_mov_b32 m0, s14
	s_lshl_b64 s[14:15], s[58:59], 11
	s_add_u32 s14, s21, s14
	v_lshl_add_u64 v[16:17], s[4:5], 0, v[136:137]
	s_addc_u32 s15, s27, s15
	v_add_u32_e32 v160, 0x14000, v150
	v_lshl_add_u64 v[16:17], v[16:17], 0, v[8:9]
	v_lshl_add_u64 v[18:19], s[14:15], 0, v[132:133]
	v_readfirstlane_b32 s21, v160
	v_add_u32_e32 v161, 0x16000, v150
	global_load_lds_dwordx4 v[16:17], off
	v_lshl_add_u64 v[18:19], v[18:19], 0, v[6:7]
	s_mov_b32 m0, s21
	v_lshl_add_u64 v[20:21], s[14:15], 0, v[136:137]
	v_readfirstlane_b32 s14, v161
	global_load_lds_dwordx4 v[18:19], off
	s_mov_b32 m0, s14
	s_add_u32 s14, s4, 0x40000
	s_addc_u32 s15, s5, 0
	v_add_u32_e32 v162, 0x4000, v150
	v_lshl_add_u64 v[20:21], v[20:21], 0, v[8:9]
	v_lshl_add_u64 v[22:23], s[14:15], 0, v[132:133]
	v_readfirstlane_b32 s21, v162
	global_load_lds_dwordx4 v[20:21], off
	v_lshl_add_u64 v[22:23], v[22:23], 0, v[6:7]
	s_mov_b32 m0, s21
	v_add_u32_e32 v163, 0x6000, v150
	global_load_lds_dwordx4 v[22:23], off
	v_lshl_add_u64 v[22:23], s[14:15], 0, v[136:137]
	v_readfirstlane_b32 s14, v163
	v_lshl_add_u64 v[22:23], v[22:23], 0, v[8:9]
	s_mov_b32 m0, s14
	v_ashrrev_i32_e32 v5, 8, v3
	global_load_lds_dwordx4 v[22:23], off
	v_cmp_eq_u32_e32 vcc, 1, v5
	s_and_saveexec_b64 s[14:15], vcc
	s_cbranch_execz .LBB0_191
	s_barrier

; #define WAIT_V8(n) asm volatile("s_waitcnt vmcnt(" #n ")" ::: "memory")
; #define BAR8 __builtin_amdgcn_s_barrier()
; #define G_SSCQ ((float*)(wsp() + OFF_SSCQ))
; #define G_SSCKV ((float*)(wsp() + OFF_SSCKV))
;     ...
;     STAGE8(SB8(0, 0), Bt, K, bcol, 0); STAGE8(SA8(0, 0), A, lda, brow, 0);
;     STAGE8(SB8(0, 1), Bt, K, bcol + 128, 0); STAGE8(SA8(0, 1), A, lda, brow + 128, 0);
;   }
;   if (wr == 1) BAR8;
;   WAIT_V8(4); BAR8;
;   STAGE8(SB8(1, 0), Bt, K, bcol, 1); STAGE8(SA8(1, 0), A, lda, brow, 1); STAGE8(SB8(1, 1), Bt, K, bcol + 128, 1);
; __global__ void __launch_bounds__(512, 2) mega(Params p) {
;     ...
;         } else {
;           e.ss_cq = G_SSCQ; e.ss_ckv = G_SSCKV;
;           gemm_tile<EPI_IN_CD, 256, true>(G_XB, DM, wb + W_IN, DM, mt * 256, nt * 256, e);
.LBB0_238:
	s_and_b64 vcc, exec, s[0:1]
	s_cbranch_vccz .LBB0_187
	s_mov_b32 s0, 25
	s_ashr_i32 s1, s0, 31
	s_lshl_b64 s[0:1], s[0:1], 3
	s_add_u32 s0, s70, s0
	s_addc_u32 s1, s71, s1
	v_readlane_b32 s2, v255, 60
	v_readlane_b32 s3, v255, 61
	s_nop 4
	s_mov_b32 s0, 25
	s_ashr_i32 s1, s0, 31
	s_lshl_b64 s[0:1], s[0:1], 3
	s_add_u32 s0, s70, s0
	s_addc_u32 s1, s71, s1
	v_readlane_b32 s4, v255, 60
	v_readlane_b32 s5, v255, 61
	s_nop 4
	s_mov_b32 s0, 25
	s_ashr_i32 s1, s0, 31
	s_lshl_b64 s[0:1], s[0:1], 3
	s_add_u32 s0, s70, s0
	s_addc_u32 s1, s71, s1
	v_mov_b32_e32 v3, v224
	v_readlane_b32 s14, v255, 60
	v_readlane_b32 s15, v255, 61
	s_nop 4
	s_ashr_i32 s53, s52, 31
	v_bfe_i32 v1, v3, 27, 1
	s_waitcnt vmcnt(10)
	v_lshlrev_b32_e32 v150, 4, v3
	v_lshrrev_b32_e32 v1, 22, v1
	v_add_u32_e32 v1, v150, v1
	v_and_b32_e32 v1, 0xfffffc00, v1
	v_ashrrev_i32_e32 v0, 31, v3
	v_sub_u32_e32 v1, v150, v1
	v_lshrrev_b32_e32 v0, 26, v0
	v_lshrrev_b32_e32 v5, 4, v1
	v_add_u32_e32 v0, v3, v0
	v_bitop3_b32 v5, v5, v1, 32 bitop3:0x6c
	v_ashrrev_i32_e32 v1, 31, v1
	v_ashrrev_i32_e32 v0, 6, v0
	v_lshrrev_b32_e32 v1, 26, v1
	v_lshlrev_b32_e32 v6, 3, v0
	v_add_u32_e32 v1, v5, v1
	v_and_b32_e32 v6, -16, v6
	v_ashrrev_i32_e32 v1, 6, v1
	v_add_u32_e32 v6, v1, v6
	v_mul_i32_i24_e32 v1, 64, v1
	v_lshlrev_b32_e32 v0, 5, v0
	v_sub_u32_e32 v1, v5, v1
	v_mov_b32_e32 v14, 1
	s_waitcnt vmcnt(9)
	v_add_u32_e32 v155, 0x2000, v150
	s_lshl_b64 s[0:1], s[52:53], 11
	v_readlane_b32 s27, v254, 44
	v_and_b32_e32 v0, 32, v0
	v_ashrrev_i16_sdwa v1, v14, sext(v1) dst_sel:DWORD dst_unused:UNUSED_PAD src0_sel:DWORD src1_sel:BYTE_0
	v_ashrrev_i32_e32 v5, 31, v155
	s_add_u32 s0, s27, s0
	v_readlane_b32 s29, v254, 45
	v_add_u32_sdwa v0, v0, sext(v1) dst_sel:DWORD dst_unused:UNUSED_PAD src0_sel:DWORD src1_sel:WORD_0
	v_ashrrev_i32_e32 v7, 31, v6
	v_lshrrev_b32_e32 v5, 22, v5
	s_addc_u32 s1, s29, s1
	v_lshlrev_b64 v[132:133], 11, v[6:7]
	v_ashrrev_i32_e32 v1, 31, v0
	v_add_u32_e32 v5, v155, v5
	v_lshl_add_u64 v[8:9], s[0:1], 0, v[132:133]
	v_lshlrev_b64 v[6:7], 1, v[0:1]
	v_ashrrev_i32_e32 v5, 10, v5
	v_lshl_add_u64 v[10:11], v[8:9], 0, v[6:7]
	v_mul_i32_i24_e32 v8, 0x400, v5
	v_sub_u32_e32 v8, v155, v8
	v_lshrrev_b32_e32 v9, 4, v8
	v_bitop3_b32 v9, v9, v8, 32 bitop3:0x6c
	v_ashrrev_i32_e32 v12, 31, v9
	v_lshrrev_b32_e32 v12, 26, v12
	v_add_u32_e32 v12, v9, v12
	v_lshlrev_b32_e32 v8, 3, v5
	v_ashrrev_i32_e32 v13, 6, v12
	v_and_b32_e32 v12, 0xc0, v12
	v_and_b32_e32 v8, -16, v8
	v_lshlrev_b32_e32 v5, 5, v5
	v_sub_u32_e32 v9, v9, v12
	v_add_u32_e32 v8, v13, v8
	v_and_b32_e32 v5, 32, v5
	v_ashrrev_i16_sdwa v9, v14, sext(v9) dst_sel:DWORD dst_unused:UNUSED_PAD src0_sel:DWORD src1_sel:BYTE_0
	v_add_u32_e32 v151, 0x10000, v150
	v_add_u32_sdwa v134, v5, sext(v9) dst_sel:DWORD dst_unused:UNUSED_PAD src0_sel:DWORD src1_sel:WORD_0
	v_ashrrev_i32_e32 v9, 31, v8
	v_readfirstlane_b32 s12, v151
	v_lshlrev_b64 v[136:137], 11, v[8:9]
	s_waitcnt vmcnt(8)
	v_add_u32_e32 v158, 0x12000, v150
	v_mov_b32_e32 v4, v2
	s_mov_b32 m0, s12
	v_lshl_add_u64 v[12:13], s[0:1], 0, v[136:137]
	v_readfirstlane_b32 s0, v158
	global_load_lds_dwordx4 v[10:11], off
	s_mov_b32 m0, s0
	s_lshl_b32 s0, s20, 19
	v_ashrrev_i32_e32 v135, 31, v134
	s_waitcnt lgkmcnt(0)
	s_add_u32 s12, s14, s0
	v_lshlrev_b64 v[8:9], 1, v[134:135]
	s_addc_u32 s13, s15, 0
	v_lshl_add_u64 v[12:13], v[12:13], 0, v[8:9]
	v_lshl_add_u64 v[14:15], s[12:13], 0, v[132:133]
	v_readfirstlane_b32 s0, v150
	global_load_lds_dwordx4 v[12:13], off
	v_lshl_add_u64 v[14:15], v[14:15], 0, v[6:7]
	s_mov_b32 m0, s0
	v_readfirstlane_b32 s0, v155
	global_load_lds_dwordx4 v[14:15], off
	s_mov_b32 m0, s0
	s_or_b32 s0, s52, 0x80
	s_ashr_i32 s1, s0, 31
	s_lshl_b64 s[20:21], s[0:1], 11
	s_add_u32 s20, s27, s20
	v_lshl_add_u64 v[16:17], s[12:13], 0, v[136:137]
	s_addc_u32 s21, s29, s21
	v_add_u32_e32 v160, 0x14000, v150
	v_lshl_add_u64 v[16:17], v[16:17], 0, v[8:9]
	v_lshl_add_u64 v[18:19], s[20:21], 0, v[132:133]
	v_readfirstlane_b32 s1, v160
	v_lshl_add_u64 v[20:21], s[20:21], 0, v[136:137]
	v_add_u32_e32 v161, 0x16000, v150
	s_add_u32 s20, s12, 0x40000
	global_load_lds_dwordx4 v[16:17], off
	v_lshl_add_u64 v[18:19], v[18:19], 0, v[6:7]
	s_mov_b32 m0, s1
	v_readfirstlane_b32 s1, v161
	s_addc_u32 s21, s13, 0
	v_add_u32_e32 v162, 0x4000, v150
	global_load_lds_dwordx4 v[18:19], off
	v_lshl_add_u64 v[20:21], v[20:21], 0, v[8:9]
	s_mov_b32 m0, s1
	v_lshl_add_u64 v[22:23], s[20:21], 0, v[132:133]
	v_readfirstlane_b32 s1, v162
	global_load_lds_dwordx4 v[20:21], off
	v_lshl_add_u64 v[22:23], v[22:23], 0, v[6:7]
	s_mov_b32 m0, s1
	v_add_u32_e32 v163, 0x6000, v150
	global_load_lds_dwordx4 v[22:23], off
	v_lshl_add_u64 v[22:23], s[20:21], 0, v[136:137]
	v_readfirstlane_b32 s1, v163
	v_lshl_add_u64 v[22:23], v[22:23], 0, v[8:9]
	s_mov_b32 m0, s1
	v_ashrrev_i32_e32 v5, 8, v3
	global_load_lds_dwordx4 v[22:23], off
	v_cmp_eq_u32_e32 vcc, 1, v5
	s_and_saveexec_b64 s[20:21], vcc
	s_cbranch_execz .LBB0_241
	s_barrier

; DI unsigned char* wsp() { return (unsigned char*)inp(25); }
; DI void convert_layer(int L, int vb, int vnb) {
;   bf16_t* wb = (bf16_t*)(wsp() + OFF_W) + (size_t)(L & 1) * WSZ;
;   const int j = L >> 1;
;   int off = 0;
;   if ((L & 1) == 0) {
;     convert_mat(inp(3) + (size_t)j * 1024 * 1536, 1024, 1536, inp(2) + L * 1024, wb + W_IN, 0, off, vb, vnb, true);
;     convert_mat(inp(7) + (size_t)j * 1024 * 1024, 1024, 1024, nullptr, wb + W_OUT, 0, off, vb, vnb);
;   } else {
;     convert_mat(inp(8) + (size_t)j * 1024 * 1952, 1024, 1952, inp(2) + L * 1024, wb + W_IN, 1, off, vb, vnb, true);
;     convert_mat(inp(11) + (size_t)j * 256 * 768, 256, 768, inp(9) + j * 256, wb + W_UQ, 0, off, vb, vnb);
;     convert_mat(inp(12) + (size_t)j * 128 * 1024, 128, 1024, inp(10) + j * 128, wb + W_UKV, 0, off, vb, vnb);
; __global__ void __launch_bounds__(512, 2) mega(Params p) {
;     ...
;       if (L < 3) { if (odd || nb < 256) convert_layer(L + 1, bid, nb); else if (bid >= 128) convert_layer(L + 1, bid - 128, nb - 128); }
.LBB0_263:
	v_readlane_b32 s0, v254, 41
	s_cmp_lg_u32 s0, 3
	s_cbranch_scc0 .LBB0_490
	v_readlane_b32 s0, v253, 27
	v_readlane_b32 s1, v253, 28
	s_or_b64 s[0:1], s[0:1], s[38:39]
	s_andn2_b64 vcc, exec, s[0:1]
	s_mov_b64 s[0:1], -1
	s_cbranch_vccz .LBB0_367
	v_readlane_b32 s0, v253, 29
	v_readlane_b32 s1, v253, 30
	s_andn2_b64 vcc, exec, s[0:1]
	s_cbranch_vccnz .LBB0_366
	s_mov_b32 s2, 25
	v_readlane_b32 s0, v254, 41
	s_ashr_i32 s3, s2, 31
	s_or_b32 s0, s0, 1
	s_lshl_b64 s[2:3], s[2:3], 3
	s_add_u32 s2, s70, s2
	s_addc_u32 s3, s71, s3
	v_readlane_b32 s2, v255, 60
	v_readlane_b32 s3, v255, 61
	s_nop 4
	v_readlane_b32 s12, v254, 35
	v_readlane_b32 s14, v254, 37
	v_readlane_b32 s15, v254, 38
	v_readlane_b32 s14, v253, 45
	v_readlane_b32 s13, v254, 36
	s_mov_b32 s4, s12
	v_readlane_b32 s15, v253, 46
	s_mov_b32 s7, s12
	s_lshl_b32 s12, s0, 10
	s_mov_b32 s13, s4
	s_mov_b32 s20, 8
	s_mov_b32 s4, 2
	s_andn2_b64 vcc, exec, s[14:15]
	s_cbranch_vccnz .LBB0_279
	s_waitcnt lgkmcnt(0)
	s_add_u32 s14, s2, 0xdb20000
	s_addc_u32 s15, s3, 0
	s_ashr_i32 s21, s20, 31
	s_lshl_b64 s[20:21], s[20:21], 3
	s_add_u32 s20, s70, s20
	s_addc_u32 s21, s71, s21
	s_load_dwordx2 s[20:21], s[20:21], 0x0
	s_mul_i32 s5, s6, 0x7a0000
	s_mul_hi_u32 s1, s6, 0x7a0000
	v_readlane_b32 s29, v253, 44
	s_waitcnt lgkmcnt(0)
	s_add_u32 s20, s20, s5
	s_addc_u32 s21, s21, s1
	s_ashr_i32 s5, s4, 31
	s_lshl_b64 s[4:5], s[4:5], 3
	s_add_u32 s4, s70, s4
	s_addc_u32 s5, s71, s5
	s_load_dwordx2 s[4:5], s[4:5], 0x0
	s_lshl_b64 s[24:25], s[12:13], 2
	s_waitcnt lgkmcnt(0)
	s_add_u32 s24, s4, s24
	s_addc_u32 s25, s5, s25
	s_cmp_lg_u64 s[4:5], 0
	v_readlane_b32 s4, v253, 47
	s_cselect_b64 s[30:31], -1, 0
	s_lshl_b32 s1, s29, 7
	s_lshl_b32 s27, s4, 7
	s_branch .LBB0_269

; DI unsigned char* wsp() { return (unsigned char*)inp(25); }
; DI void convert_layer(int L, int vb, int vnb) {
;   bf16_t* wb = (bf16_t*)(wsp() + OFF_W) + (size_t)(L & 1) * WSZ;
;   const int j = L >> 1;
;   int off = 0;
;   if ((L & 1) == 0) {
;     convert_mat(inp(3) + (size_t)j * 1024 * 1536, 1024, 1536, inp(2) + L * 1024, wb + W_IN, 0, off, vb, vnb, true);
;     convert_mat(inp(7) + (size_t)j * 1024 * 1024, 1024, 1024, nullptr, wb + W_OUT, 0, off, vb, vnb);
;   } else {
;     convert_mat(inp(8) + (size_t)j * 1024 * 1952, 1024, 1952, inp(2) + L * 1024, wb + W_IN, 1, off, vb, vnb, true);
; __global__ void __launch_bounds__(512, 2) mega(Params p) {
;     ...
;       if (L < 3) { if (odd || nb < 256) convert_layer(L + 1, bid, nb); else if (bid >= 128) convert_layer(L + 1, bid - 128, nb - 128); }
.LBB0_367:
	s_andn2_b64 vcc, exec, s[0:1]
	s_cbranch_vccnz .LBB0_490
	v_readlane_b32 s0, v254, 41
	s_add_i32 s30, s0, 1
	s_mov_b32 s0, 25
	s_ashr_i32 s1, s0, 31
	s_lshl_b64 s[0:1], s[0:1], 3
	s_add_u32 s0, s70, s0
	s_addc_u32 s1, s71, s1
	s_waitcnt lgkmcnt(0)
	v_readlane_b32 s2, v255, 60
	v_readlane_b32 s3, v255, 61
	s_nop 4
	s_and_b32 s0, s30, 1
	s_mul_i32 s0, s0, 0x1b20000
	v_readlane_b32 s44, v254, 35
	s_mov_b32 s43, s44
	s_waitcnt lgkmcnt(0)
	s_add_u32 s0, s2, s0
	s_addc_u32 s1, s3, 0
	s_add_u32 s40, s0, 0xc000000
	s_addc_u32 s41, s1, 0
	s_lshr_b32 s0, s30, 1
	s_bitcmp1_b32 s30, 0
	s_cselect_b64 s[12:13], -1, 0
	s_mov_b32 s1, s44
	s_lshl_b32 s42, s30, 10
	s_mov_b64 s[4:5], -1
	s_and_b64 vcc, exec, s[12:13]
	v_readlane_b32 s45, v254, 36
	v_readlane_b32 s46, v254, 37
	v_readlane_b32 s47, v254, 38
	s_cbranch_vccz .LBB0_417
	v_readlane_b32 s14, v253, 32
	v_readlane_b32 s15, v253, 33
	s_mov_b32 s12, 8
	s_mov_b32 s4, 2
	s_andn2_b64 vcc, exec, s[14:15]
	s_cbranch_vccnz .LBB0_382
	s_ashr_i32 s13, s12, 31
	s_lshl_b64 s[12:13], s[12:13], 3
	s_add_u32 s12, s70, s12
	s_addc_u32 s13, s71, s13
	s_load_dwordx2 s[12:13], s[12:13], 0x0
	s_mul_i32 s7, s0, 0x7a0000
	s_mul_hi_u32 s5, s0, 0x7a0000
	v_readlane_b32 s29, v252, 12
	s_waitcnt lgkmcnt(0)
	s_add_u32 s12, s12, s7
	s_addc_u32 s13, s13, s5
	s_ashr_i32 s5, s4, 31
	s_lshl_b64 s[4:5], s[4:5], 3
	s_add_u32 s4, s70, s4
	s_addc_u32 s5, s71, s5
	s_load_dwordx2 s[4:5], s[4:5], 0x0
	s_lshl_b64 s[14:15], s[42:43], 2
	s_waitcnt lgkmcnt(0)
	s_add_u32 s14, s4, s14
	s_addc_u32 s15, s5, s15
	s_cmp_lg_u64 s[4:5], 0
	v_readlane_b32 s4, v252, 1
	s_cselect_b64 s[20:21], -1, 0
	s_lshl_b32 s7, s29, 7
	s_lshl_b32 s27, s4, 7
	v_readlane_b32 s5, v252, 2
	s_branch .LBB0_372

; #define WAIT_V0() asm volatile("s_waitcnt vmcnt(0)" ::: "memory")
; #define G_SSCKV ((float*)(wsp() + OFF_SSCKV))
; template <int EPI, int BN, bool F16>
; DI void gemm_tile(const bf16_t* __restrict__ A, int lda, const bf16_t* __restrict__ W, int K, int m0, int n0, const Ep& e) {
;     ...
;   const int grow = w * 8 + (l >> 3);
;   const int gch = (l & 7) ^ ((grow >> 1) & 7);
;   const bf16_t* ap = A + (size_t)(m0 + grow) * lda + gch * 8;
;   const bf16_t* wp = W + (size_t)(n0 + grow) * K + gch * 8;
;   unsigned char* lbase = smem + w * 1024;
;   const int sw = (r >> 1) & 7;
;   const unsigned char* ab = smem + (wm * (MI * 32) + r) * 128;
;   const unsigned char* bb = smem + 32768 + (wn * 64 + r) * 128;
;   const int nk = K >> 6;
;     ...
;   G_STAGE(0, 0)
;   WAIT_V0();
;   __syncthreads();
;   for (int kt = 0; kt < nk; kt += 2) {
;     G_STAGE(1, kt + 1)
;     G_COMPUTE(0)
;     WAIT_V0();
;     __syncthreads();
;     if (kt + 2 < nk) { G_STAGE(0, kt + 2) }
;     G_COMPUTE(1)
;     WAIT_V0();
;     __syncthreads();
; __global__ void __launch_bounds__(512, 2) mega(Params p) {
;     ...
;           const int it = item - 192;
;           const int nt = it >> 6, mt = it & 63;
;           e.ss = G_SSCKV; e.nss = 2; e.inv_n = 1.f / 128.f; e.out = G_KVC; e.ldo = 1024;
;           gemm_tile<EPI_PLAIN, 128, false>(G_ZB + 256, ZLD, wb + W_UKV, 128, mt * 256, nt * 128, e);
.LBB0_547:
	s_cmpk_gt_i32 s33, 0xbf
	s_mov_b64 s[0:1], -1
	s_cbranch_scc0 .LBB0_551
	s_mov_b32 s12, 25
	s_mov_b32 s0, 25
	s_ashr_i32 s1, s0, 31
	s_lshl_b64 s[0:1], s[0:1], 3
	s_add_u32 s0, s70, s0
	s_addc_u32 s1, s71, s1
	v_readlane_b32 s2, v255, 60
	v_readlane_b32 s3, v255, 61
	s_nop 4
	s_mov_b32 s0, 25
	s_ashr_i32 s1, s0, 31
	s_lshl_b64 s[0:1], s[0:1], 3
	s_add_u32 s0, s70, s0
	s_addc_u32 s1, s71, s1
	v_mov_b32_e32 v0, v224
	v_readlane_b32 s14, v255, 60
	v_readlane_b32 s15, v255, 61
	s_nop 4
	s_and_b32 s0, s24, 0x7fffff80
	v_ashrrev_i32_e32 v3, 6, v0
	v_bfe_u32 v4, v0, 3, 3
	v_lshl_or_b32 v10, v3, 3, v4
	s_and_b32 s27, s25, 0x3f00
	s_addk_i32 s0, 0xfe80
	v_lshrrev_b32_e32 v4, 1, v10
	v_xor_b32_e32 v6, v4, v0
	v_add_u32_e32 v4, s27, v10
	v_add_u32_e32 v10, s0, v10
	v_ashrrev_i32_e32 v5, 31, v4
	v_ashrrev_i32_e32 v11, 31, v10
	v_lshlrev_b64 v[4:5], 12, v[4:5]
	v_lshlrev_b32_e32 v6, 4, v6
	v_lshlrev_b64 v[10:11], 8, v[10:11]
	s_waitcnt lgkmcnt(0)
	v_lshl_add_u64 v[4:5], s[14:15], 0, v[4:5]
	v_and_b32_e32 v6, 0x70, v6
	v_mov_b32_e32 v7, v2
	v_lshl_add_u64 v[10:11], s[4:5], 0, v[10:11]
	v_lshl_add_u64 v[4:5], v[4:5], 0, v[6:7]
	v_lshl_add_u64 v[6:7], v[10:11], 0, v[6:7]
	v_lshlrev_b32_e32 v10, 10, v3
	v_ashrrev_i32_e32 v3, 1, v0
	v_and_b32_e32 v1, 31, v0
	s_mov_b64 s[14:15], 0x2000200
	v_and_b32_e32 v3, 0xffffffc0, v3
	v_readfirstlane_b32 s1, v10
	v_lshl_add_u64 v[8:9], v[4:5], 0, s[14:15]
	v_or_b32_e32 v12, v3, v1
	s_mov_b32 m0, s1
	v_lshlrev_b32_e32 v69, 7, v12
	v_lshlrev_b32_e32 v12, 7, v0
	global_load_lds_dwordx4 v[8:9], off
	v_add_u32_e32 v8, 0x8000, v10
	v_and_b32_e32 v102, 0x2f80, v12
	v_readfirstlane_b32 s1, v8
	v_add_u32_e32 v12, 0x2000, v10
	s_mov_b32 m0, s1
	s_mov_b64 s[14:15], 0x2040200
	v_readfirstlane_b32 s1, v12
	v_add_u32_e32 v12, 0xa000, v10
	global_load_lds_dwordx4 v[6:7], off
	v_lshl_add_u64 v[8:9], v[4:5], 0, s[14:15]
	s_mov_b32 m0, s1
	s_mov_b64 s[14:15], 0x4000
	v_readfirstlane_b32 s1, v12
	v_add_u32_e32 v12, 0x4000, v10
	global_load_lds_dwordx4 v[8:9], off
	v_lshl_add_u64 v[8:9], v[6:7], 0, s[14:15]
	s_mov_b32 m0, s1
	s_mov_b64 s[14:15], 0x2080200
	v_readfirstlane_b32 s1, v12
	v_add_u32_e32 v12, 0x6000, v10
	global_load_lds_dwordx4 v[8:9], off
	v_lshl_add_u64 v[8:9], v[4:5], 0, s[14:15]
	s_mov_b32 m0, s1
	s_mov_b64 s[14:15], 0x20c0200
	v_readfirstlane_b32 s1, v12
	v_lshrrev_b32_e32 v11, 1, v0
	global_load_lds_dwordx4 v[8:9], off
	v_lshl_add_u64 v[8:9], v[4:5], 0, s[14:15]
	s_mov_b32 m0, s1
	v_bfe_u32 v68, v0, 5, 1
	global_load_lds_dwordx4 v[8:9], off
	v_bfe_u32 v103, v0, 1, 3
	v_add_u32_e32 v12, 0x10000, v10
	v_bitop3_b32 v8, v68, v11, 7 bitop3:0x78
	v_lshlrev_b32_e32 v104, 4, v8
	v_bitop3_b32 v8, v68, v103, 2 bitop3:0x36
	s_mov_b64 s[14:15], 0x2000280
	v_readfirstlane_b32 s1, v12
	v_add_u32_e32 v12, 0x18000, v10
	v_lshlrev_b32_e32 v105, 4, v8
	v_lshl_add_u64 v[8:9], v[4:5], 0, s[14:15]
	s_mov_b32 m0, s1
	s_mov_b64 s[14:15], 0x80
	v_readfirstlane_b32 s1, v12
	v_add_u32_e32 v12, 0x12000, v10
	s_waitcnt vmcnt(0)
	s_waitcnt vmcnt(0) lgkmcnt(0)
	s_barrier
	global_load_lds_dwordx4 v[8:9], off
	v_lshl_add_u64 v[8:9], v[6:7], 0, s[14:15]
	s_mov_b32 m0, s1
	s_mov_b64 s[14:15], 0x2040280
	v_readfirstlane_b32 s1, v12
	global_load_lds_dwordx4 v[8:9], off
	v_lshl_add_u64 v[8:9], v[4:5], 0, s[14:15]
	s_mov_b32 m0, s1
	s_mov_b64 s[14:15], 0x4080
	global_load_lds_dwordx4 v[8:9], off
	v_add_u32_e32 v8, 0x1a000, v10
	v_lshl_add_u64 v[6:7], v[6:7], 0, s[14:15]
	v_readfirstlane_b32 s1, v8
	v_add_u32_e32 v8, 0x14000, v10
	s_mov_b32 m0, s1
	s_mov_b64 s[14:15], 0x2080280
	v_readfirstlane_b32 s1, v8
	global_load_lds_dwordx4 v[6:7], off
	v_lshl_add_u64 v[6:7], v[4:5], 0, s[14:15]
	s_mov_b32 m0, s1
	s_mov_b64 s[14:15], 0x20c0280
	global_load_lds_dwordx4 v[6:7], off
	v_add_u32_e32 v6, 0x16000, v10
	v_lshl_add_u64 v[4:5], v[4:5], 0, s[14:15]
	v_readfirstlane_b32 s1, v6
	s_mov_b32 m0, s1
	v_or_b32_e32 v32, v69, v104
	global_load_lds_dwordx4 v[4:5], off
	v_or_b32_e32 v4, v102, v105
	v_or_b32_e32 v11, v69, v105
	ds_read_b128 v[70:73], v4 offset:36864
	ds_read_b128 v[74:77], v4 offset:32768
	v_or_b32_e32 v4, v102, v104
	ds_read_b128 v[78:81], v11 offset:4096
	ds_read_b128 v[82:85], v11
	ds_read_b128 v[20:23], v4 offset:36864
	ds_read_b128 v[24:27], v4 offset:32768
	ds_read_b128 v[28:31], v32 offset:4096
	s_waitcnt lgkmcnt(0)
	v_mfma_f32_32x32x16_bf16 v[4:19], v[28:31], v[24:27], 0
	ds_read_b128 v[32:35], v32
	s_movk_i32 s1, 0x100
	v_cmp_gt_i32_e32 vcc, s1, v0
	s_waitcnt lgkmcnt(0)
	v_mfma_f32_32x32x16_bf16 v[36:51], v[32:35], v[24:27], 0
	v_bitop3_b32 v24, v68, v103, 4 bitop3:0x36
	v_lshlrev_b32_e32 v106, 4, v24
	v_or_b32_e32 v24, v69, v106
	ds_read_b128 v[86:89], v24
	v_or_b32_e32 v98, v102, v106
	v_mfma_f32_32x32x16_bf16 v[52:67], v[32:35], v[20:23], 0
	ds_read_b128 v[90:93], v24 offset:4096
	v_mfma_f32_32x32x16_bf16 v[20:35], v[28:31], v[20:23], 0
	ds_read_b128 v[94:97], v98 offset:32768
	v_mfma_f32_32x32x16_bf16 v[36:51], v[82:85], v[74:77], v[36:51]
	ds_read_b128 v[98:101], v98 offset:36864
	v_mfma_f32_32x32x16_bf16 v[52:67], v[82:85], v[70:73], v[52:67]
	v_bitop3_b32 v82, v68, v103, 6 bitop3:0x36
	v_lshlrev_b32_e32 v103, 4, v82
	v_or_b32_e32 v107, v69, v103
	ds_read_b128 v[82:85], v107
	v_add_u32_e32 v69, 0x10000, v69
	v_mfma_f32_32x32x16_bf16 v[4:19], v[78:81], v[74:77], v[4:19]
	ds_read_b128 v[74:77], v107 offset:4096
	v_or_b32_e32 v107, v69, v104
	v_mfma_f32_32x32x16_bf16 v[20:35], v[78:81], v[70:73], v[20:35]
	v_or_b32_e32 v78, v102, v103
	ds_read_b128 v[70:73], v78 offset:32768
	v_or_b32_e32 v102, 0x18000, v102
	s_waitcnt lgkmcnt(0)
	v_mfma_f32_32x32x16_bf16 v[36:51], v[86:89], v[94:97], v[36:51]
	ds_read_b128 v[78:81], v78 offset:36864
	s_waitcnt vmcnt(0)
	s_waitcnt vmcnt(0) lgkmcnt(0)
	s_barrier
; #define WAIT_V0() asm volatile("s_waitcnt vmcnt(0)" ::: "memory")
; template <int EPI, int BN, bool F16>
; DI void gemm_tile(const bf16_t* __restrict__ A, int lda, const bf16_t* __restrict__ W, int K, int m0, int n0, const Ep& e) {
;     ...
;   for (int kt = 0; kt < nk; kt += 2) {
;     G_STAGE(1, kt + 1)
;     G_COMPUTE(0)
;     WAIT_V0();
;     __syncthreads();
;     if (kt + 2 < nk) { G_STAGE(0, kt + 2) }
;     G_COMPUTE(1)
;     WAIT_V0();
;     __syncthreads();
;   }
;     ...
;   if (t < 256) {
;     float rs = 1.f;
;     if (e.ss) {
;       const float* sp = e.ss + (size_t)(m0 + t) * e.nss;
;       float s = 0.f;
;       for (int i = 0; i < e.nss; ++i) s += sp[i];
;       rs = rsqrtf(s * e.inv_n + EPS);
;     }
;     ((float*)(smem + SMEM_RSTD))[t] = rs;
	v_mfma_f32_32x32x16_bf16 v[52:67], v[86:89], v[98:101], v[52:67]
	v_mfma_f32_32x32x16_bf16 v[4:19], v[90:93], v[94:97], v[4:19]
	ds_read_b128 v[94:97], v107 offset:4096
	v_mfma_f32_32x32x16_bf16 v[20:35], v[90:93], v[98:101], v[20:35]
	v_or_b32_e32 v98, v102, v104
	ds_read_b128 v[90:93], v98
	ds_read_b128 v[98:101], v98 offset:4096
	v_or_b32_e32 v104, v69, v105
	v_mfma_f32_32x32x16_bf16 v[20:35], v[74:77], v[78:81], v[20:35]
	s_waitcnt lgkmcnt(0)
	v_mfma_f32_32x32x16_bf16 v[20:35], v[94:97], v[98:101], v[20:35]
	v_mfma_f32_32x32x16_bf16 v[36:51], v[82:85], v[70:73], v[36:51]
	v_mfma_f32_32x32x16_bf16 v[52:67], v[82:85], v[78:81], v[52:67]
	v_or_b32_e32 v78, v102, v105
	v_mfma_f32_32x32x16_bf16 v[4:19], v[74:77], v[70:73], v[4:19]
	ds_read_b128 v[70:73], v104 offset:4096
	ds_read_b128 v[74:77], v78
	ds_read_b128 v[78:81], v78 offset:4096
	s_waitcnt lgkmcnt(0)
	v_mfma_f32_32x32x16_bf16 v[20:35], v[70:73], v[78:81], v[20:35]
	v_mfma_f32_32x32x16_bf16 v[4:19], v[94:97], v[90:93], v[4:19]
	v_mfma_f32_32x32x16_bf16 v[4:19], v[70:73], v[74:77], v[4:19]
	ds_read_b128 v[86:89], v107
	s_waitcnt lgkmcnt(0)
	v_mfma_f32_32x32x16_bf16 v[52:67], v[86:89], v[98:101], v[52:67]
	ds_read_b128 v[82:85], v104
	s_waitcnt lgkmcnt(0)
	v_mfma_f32_32x32x16_bf16 v[52:67], v[82:85], v[78:81], v[52:67]
	v_or_b32_e32 v78, v102, v106
	v_mfma_f32_32x32x16_bf16 v[36:51], v[86:89], v[90:93], v[36:51]
	v_mfma_f32_32x32x16_bf16 v[36:51], v[82:85], v[74:77], v[36:51]
	v_or_b32_e32 v82, v69, v106
	ds_read_b128 v[70:73], v82
	ds_read_b128 v[74:77], v78
	ds_read_b128 v[78:81], v78 offset:4096
	v_or_b32_e32 v69, v69, v103
	s_waitcnt lgkmcnt(1)
	v_mfma_f32_32x32x16_bf16 v[36:51], v[70:73], v[74:77], v[36:51]
	s_waitcnt lgkmcnt(0)
	v_mfma_f32_32x32x16_bf16 v[52:67], v[70:73], v[78:81], v[52:67]
	ds_read_b128 v[70:73], v82 offset:4096
	s_waitcnt lgkmcnt(0)
	v_mfma_f32_32x32x16_bf16 v[4:19], v[70:73], v[74:77], v[4:19]
	v_mfma_f32_32x32x16_bf16 v[20:35], v[70:73], v[78:81], v[20:35]
	ds_read_b128 v[70:73], v69
	v_or_b32_e32 v78, v102, v103
	ds_read_b128 v[74:77], v78
	ds_read_b128 v[78:81], v78 offset:4096
	s_waitcnt lgkmcnt(1)
	v_mfma_f32_32x32x16_bf16 v[36:51], v[70:73], v[74:77], v[36:51]
	s_waitcnt lgkmcnt(0)
	v_mfma_f32_32x32x16_bf16 v[52:67], v[70:73], v[78:81], v[52:67]
	ds_read_b128 v[70:73], v69 offset:4096
	s_waitcnt vmcnt(0)
	s_waitcnt lgkmcnt(0)
	s_barrier
	v_mfma_f32_32x32x16_bf16 v[4:19], v[70:73], v[74:77], v[4:19]
	v_mfma_f32_32x32x16_bf16 v[20:35], v[70:73], v[78:81], v[20:35]
	s_and_saveexec_b64 s[14:15], vcc
	s_cbranch_execz .LBB0_550
	s_ashr_i32 s13, s12, 31
	s_lshl_b64 s[12:13], s[12:13], 3
	s_add_u32 s12, s70, s12
	s_addc_u32 s13, s71, s13
	s_load_dwordx2 s[12:13], s[12:13], 0x0
	v_add_u32_e32 v70, s27, v0
	v_ashrrev_i32_e32 v71, 31, v70
	s_mov_b32 s1, 0xf782000
	s_waitcnt lgkmcnt(0)
	v_lshl_add_u64 v[70:71], v[70:71], 3, s[12:13]
	v_add_co_u32_e32 v70, vcc, s1, v70
	s_mov_b32 s1, 0x800000
	s_nop 0
	v_addc_co_u32_e32 v71, vcc, 0, v71, vcc
	global_load_dwordx2 v[70:71], v[70:71], off
	s_waitcnt vmcnt(0)
	v_add_f32_e32 v69, 0, v70
	v_add_f32_e32 v69, v69, v71
	v_mov_b32_e32 v70, 0x358637bd
	v_fmamk_f32 v69, v69, 0x3c000000, v70
	v_mul_f32_e32 v70, 0x4b800000, v69
	v_cmp_gt_f32_e32 vcc, s1, v69
	s_nop 1
	v_cndmask_b32_e32 v69, v69, v70, vcc
	v_rsq_f32_e32 v69, v69
	s_nop 0
	v_mul_f32_e32 v70, 0x45800000, v69
	v_cndmask_b32_e32 v69, v69, v70, vcc
	v_lshl_add_u32 v70, v0, 2, v234
	ds_write_b32 v70, v69

; #define WAIT_V8(n) asm volatile("s_waitcnt vmcnt(" #n ")" ::: "memory")
; #define BAR8 __builtin_amdgcn_s_barrier()
; #define G_SSCQ ((float*)(wsp() + OFF_SSCQ))
;     ...
;     STAGE8(SB8(0, 0), Bt, K, bcol, 0); STAGE8(SA8(0, 0), A, lda, brow, 0);
;     STAGE8(SB8(0, 1), Bt, K, bcol + 128, 0); STAGE8(SA8(0, 1), A, lda, brow + 128, 0);
;   }
;   if (wr == 1) BAR8;
;   WAIT_V8(4); BAR8;
;   STAGE8(SB8(1, 0), Bt, K, bcol, 1); STAGE8(SA8(1, 0), A, lda, brow, 1); STAGE8(SB8(1, 1), Bt, K, bcol + 128, 1);
; __global__ void __launch_bounds__(512, 2) mega(Params p) {
;     ...
;         if (item < 192) {
;           const int nt = item >> 6, mt = item & 63;
;           e.ss = G_SSCQ; e.nss = 4; e.inv_n = 1.f / 256.f; e.out = G_QC; e.ldo = 768;
;           gemm_tile<EPI_UQ, 256, false>(G_ZB, ZLD, wb + W_UQ, 256, mt * 256, nt * 256, e);
.LBB0_551:
	s_and_b64 vcc, exec, s[0:1]
	s_cbranch_vccz .LBB0_546
	s_mov_b32 s0, 25
	s_ashr_i32 s1, s0, 31
	s_lshl_b64 s[0:1], s[0:1], 3
	s_add_u32 s0, s70, s0
	s_addc_u32 s1, s71, s1
	v_readlane_b32 s2, v255, 60
	v_readlane_b32 s3, v255, 61
	s_nop 4
	s_mov_b32 s0, 25
	s_ashr_i32 s1, s0, 31
	s_lshl_b64 s[0:1], s[0:1], 3
	s_add_u32 s0, s70, s0
	s_addc_u32 s1, s71, s1
	s_mov_b32 s12, 25
	v_readlane_b32 s0, v255, 60
	v_readlane_b32 s1, v255, 61
	s_nop 4
	s_ashr_i32 s13, s12, 31
	s_lshl_b64 s[12:13], s[12:13], 3
	s_add_u32 s12, s70, s12
	s_addc_u32 s13, s71, s13
	v_mov_b32_e32 v3, v224
	v_readlane_b32 s12, v255, 60
	v_readlane_b32 s13, v255, 61
	s_nop 4
	s_and_b32 s30, s21, 0xffffff00
	v_bfe_i32 v1, v3, 27, 1
	v_lshlrev_b32_e32 v26, 4, v3
	v_lshrrev_b32_e32 v1, 22, v1
	v_add_u32_e32 v1, v26, v1
	v_and_b32_e32 v1, 0xfffffc00, v1
	v_ashrrev_i32_e32 v0, 31, v3
	v_sub_u32_e32 v1, v26, v1
	v_lshrrev_b32_e32 v0, 26, v0
	v_lshrrev_b32_e32 v5, 4, v1
	v_add_u32_e32 v0, v3, v0
	v_bitop3_b32 v5, v5, v1, 32 bitop3:0x6c
	v_ashrrev_i32_e32 v1, 31, v1
	v_ashrrev_i32_e32 v0, 6, v0
	v_lshrrev_b32_e32 v1, 26, v1
	v_lshlrev_b32_e32 v6, 3, v0
	v_add_u32_e32 v1, v5, v1
	v_and_b32_e32 v6, -16, v6
	v_ashrrev_i32_e32 v1, 6, v1
	v_add_u32_e32 v6, v1, v6
	v_mul_i32_i24_e32 v1, 64, v1
	s_ashr_i32 s31, s30, 31
	v_lshlrev_b32_e32 v0, 5, v0
	v_sub_u32_e32 v1, v5, v1
	v_mov_b32_e32 v13, 1
	v_add_u32_e32 v27, 0x2000, v26
	s_and_b32 s36, s25, 0x3f00
	s_lshl_b64 s[14:15], s[30:31], 9
	v_and_b32_e32 v0, 32, v0
	v_ashrrev_i16_sdwa v1, v13, sext(v1) dst_sel:DWORD dst_unused:UNUSED_PAD src0_sel:DWORD src1_sel:BYTE_0
	v_ashrrev_i32_e32 v5, 31, v27
	s_add_u32 s14, s7, s14
	v_add_u32_sdwa v0, v0, sext(v1) dst_sel:DWORD dst_unused:UNUSED_PAD src0_sel:DWORD src1_sel:WORD_0
	v_ashrrev_i32_e32 v7, 31, v6
	v_lshrrev_b32_e32 v5, 22, v5
	s_addc_u32 s15, s20, s15
	v_lshlrev_b64 v[16:17], 9, v[6:7]
	v_ashrrev_i32_e32 v1, 31, v0
	v_add_u32_e32 v5, v27, v5
	v_lshl_add_u64 v[8:9], s[14:15], 0, v[16:17]
	v_lshlrev_b64 v[0:1], 1, v[0:1]
	v_ashrrev_i32_e32 v5, 10, v5
	v_lshl_add_u64 v[14:15], v[8:9], 0, v[0:1]
	v_mul_i32_i24_e32 v8, 0x400, v5
	v_sub_u32_e32 v8, v27, v8
	v_lshrrev_b32_e32 v9, 4, v8
	v_bitop3_b32 v8, v9, v8, 32 bitop3:0x6c
	v_ashrrev_i32_e32 v10, 31, v8
	v_lshrrev_b32_e32 v10, 26, v10
	v_lshlrev_b32_e32 v9, 3, v5
	v_add_u32_e32 v10, v8, v10
	v_and_b32_e32 v9, -16, v9
	v_ashrrev_i32_e32 v11, 6, v10
	v_add_u32_e32 v12, v11, v9
	v_and_b32_e32 v9, 0xc0, v10
	v_sub_u32_e32 v8, v8, v9
	v_add_u32_e32 v30, 0x10000, v26
	v_ashrrev_i16_sdwa v8, v13, sext(v8) dst_sel:DWORD dst_unused:UNUSED_PAD src0_sel:DWORD src1_sel:BYTE_0
	v_ashrrev_i32_e32 v13, 31, v12
	v_readfirstlane_b32 s27, v30
	v_lshlrev_b64 v[18:19], 9, v[12:13]
	v_add_u32_e32 v33, 0x12000, v26
	v_mov_b32_e32 v4, v2
	s_mov_b32 m0, s27
	v_lshlrev_b32_e32 v5, 5, v5
	v_lshl_add_u64 v[10:11], s[14:15], 0, v[18:19]
	v_readfirstlane_b32 s14, v33
	global_load_lds_dwordx4 v[14:15], off
	v_and_b32_e32 v5, 32, v5
	s_mov_b32 m0, s14
	s_lshl_b32 s14, s36, 12
	v_add_u32_sdwa v8, v5, sext(v8) dst_sel:DWORD dst_unused:UNUSED_PAD src0_sel:DWORD src1_sel:WORD_0
	s_waitcnt lgkmcnt(0)
	s_add_u32 s27, s12, s14
	v_ashrrev_i32_e32 v9, 31, v8
	s_addc_u32 s29, s13, 0
	v_lshlrev_b64 v[8:9], 1, v[8:9]
	s_add_u32 s12, s27, 0x2000000
	v_lshl_add_u64 v[24:25], v[10:11], 0, v[8:9]
	s_addc_u32 s13, s29, 0
	v_lshlrev_b64 v[10:11], 12, v[6:7]
	v_lshl_add_u64 v[6:7], s[12:13], 0, v[10:11]
	v_readfirstlane_b32 s14, v26
	s_or_b32 s38, s30, 0x80
	global_load_lds_dwordx4 v[24:25], off
	v_lshl_add_u64 v[20:21], v[6:7], 0, v[0:1]
	s_mov_b32 m0, s14
	v_readfirstlane_b32 s14, v27
	s_ashr_i32 s39, s38, 31
	global_load_lds_dwordx4 v[20:21], off
	s_mov_b32 m0, s14
	s_lshl_b64 s[14:15], s[38:39], 9
	v_lshlrev_b64 v[12:13], 12, v[12:13]
	s_add_u32 s14, s7, s14
	v_lshl_add_u64 v[6:7], s[12:13], 0, v[12:13]
	s_addc_u32 s15, s20, s15
	v_add_u32_e32 v31, 0x14000, v26
	v_lshl_add_u64 v[22:23], v[6:7], 0, v[8:9]
	v_lshl_add_u64 v[6:7], s[14:15], 0, v[16:17]
	v_readfirstlane_b32 s37, v31
	v_add_u32_e32 v32, 0x16000, v26
	global_load_lds_dwordx4 v[22:23], off
	v_lshl_add_u64 v[16:17], v[6:7], 0, v[0:1]
	s_mov_b32 m0, s37
	v_lshl_add_u64 v[6:7], s[14:15], 0, v[18:19]
	v_readfirstlane_b32 s14, v32
	global_load_lds_dwordx4 v[16:17], off
	s_mov_b32 m0, s14
	s_add_u32 s14, s27, 0x2080000
	s_addc_u32 s15, s29, 0
	v_add_u32_e32 v28, 0x4000, v26
	v_lshl_add_u64 v[18:19], v[6:7], 0, v[8:9]
	v_lshl_add_u64 v[6:7], s[14:15], 0, v[10:11]
	v_readfirstlane_b32 s27, v28
	global_load_lds_dwordx4 v[18:19], off
	v_lshl_add_u64 v[6:7], v[6:7], 0, v[0:1]
	s_mov_b32 m0, s27
	v_add_u32_e32 v29, 0x6000, v26
	global_load_lds_dwordx4 v[6:7], off
	v_lshl_add_u64 v[6:7], s[14:15], 0, v[12:13]
	v_readfirstlane_b32 s14, v29
	v_lshl_add_u64 v[6:7], v[6:7], 0, v[8:9]
	s_mov_b32 m0, s14
	v_ashrrev_i32_e32 v132, 8, v3
	global_load_lds_dwordx4 v[6:7], off
	v_cmp_eq_u32_e32 vcc, 1, v132
	s_and_saveexec_b64 s[14:15], vcc
	s_cbranch_execz .LBB0_554
	s_barrier

; template <int DK, int DV, int MODE, int QB, bool PACK = false>
; DI void attn_item(const AttArgs& a, int q0, int t_lo, int t_hi) {
;     ...
;     for (int i = t; i < 465; i += NT) rpbs[i] = a.rpb[i];
; __global__ void __launch_bounds__(512, 2) mega(Params p) {
;     ...
;         const int qt = rest & 3, pg = rest >> 2;
;         const int pair = pg * 8 + pl;
;         const int b = pair >> 3, hd = pair & 7;
;         const int q0 = qt * 512;
;         const bf16_t* zrow = G_ZB + (size_t)b * SEQ * ZLD;
;         if (item < 256) {
;           a.q = G_QC + (size_t)b * SEQ * 768 + hd * 96; a.ldq = 768;
;           a.k = G_KVC + (size_t)b * SEQ * 1024 + hd * 128; a.ldk = 1024;
;           a.k2 = zrow + 384; a.ldk2 = ZLD;
;           a.v = G_KVC + (size_t)b * SEQ * 1024 + hd * 128 + 64; a.ldv = 1024;
;           a.o = G_OB + (size_t)b * SEQ * DM + hd * 64; a.ldo = DM;
;           a.scale = 0.10206207261596577f;
;           attn_item<96, 64, 3, 2>(a, q0, 0, 32);
;         } else {
;           a.q = zrow + 512 + hd * 64; a.k = zrow + 1024 + hd * 64; a.v = zrow + 1536 + hd * 64;
;           a.ldq = a.ldk = a.ldv = ZLD;
;           a.o = G_OB + (size_t)b * SEQ * DM + 512 + hd * 64; a.ldo = DM;
;           a.scale = 0.125f;
;           a.rpb = inp(13) + (size_t)(j * 8 + hd) * 465;
;           const int ra = q0 >> 6;
;           const int tlo = min(max(ra - 4, 0), 24), thi = min(max(ra + 7 - 4, 0), 24) + 8;
.LBB0_635:
	s_lshr_b32 s29, s25, 3
	s_and_b32 s38, s25, 7
	v_readlane_b32 s0, v254, 41
	s_bitcmp1_b32 s0, 0
	s_cselect_b64 s[2:3], -1, 0
	s_mov_b64 s[0:1], -1
	s_and_b64 vcc, exec, s[2:3]
	s_cbranch_vccz .LBB0_799
	s_lshl_b32 s0, s29, 9
	s_and_b32 s21, s0, 0x600
	s_mov_b32 s0, 25
	s_ashr_i32 s1, s0, 31
	s_lshl_b64 s[0:1], s[0:1], 3
	s_add_u32 s0, s70, s0
	s_addc_u32 s1, s71, s1
	v_readlane_b32 s0, v255, 60
	v_readlane_b32 s1, v255, 61
	s_nop 4
	s_lshl_b32 s2, s25, 6
	s_and_b32 s20, s2, 0x3800
	s_lshl_b32 s2, s20, 12
	v_writelane_b32 v254, s24, 52
	s_waitcnt lgkmcnt(0)
	s_add_u32 s0, s0, s2
	s_addc_u32 s1, s1, 0
	s_add_u32 s30, s0, 0x2000000
	s_addc_u32 s31, s1, 0
	v_writelane_b32 v254, s25, 53
	s_cmpk_gt_i32 s25, 0xff
	s_mov_b64 s[0:1], -1
	s_cbranch_scc0 .LBB0_752
	s_mov_b32 s0, 25
	s_ashr_i32 s1, s0, 31
	s_lshl_b64 s[0:1], s[0:1], 3
	s_add_u32 s0, s70, s0
	s_addc_u32 s1, s71, s1
	v_readlane_b32 s24, v255, 60
	v_readlane_b32 s25, v255, 61
	s_nop 4
	s_mov_b32 s2, 13
	v_mov_b32_e32 v0, v224
	s_movk_i32 s0, 0x1d1
	s_nop 0
	v_cmp_gt_i32_e32 vcc, s0, v0
	s_and_saveexec_b64 s[0:1], vcc
	s_cbranch_execz .LBB0_645
	s_ashr_i32 s3, s2, 31
	s_lshl_b64 s[2:3], s[2:3], 3
	s_add_u32 s2, s70, s2
	s_addc_u32 s3, s71, s3
	s_load_dwordx2 s[2:3], s[2:3], 0x0
	v_max_i32_e32 v1, 0xffffffd1, v0
	v_sub_u32_e32 v1, v1, v0
	v_add_u32_e32 v1, 0x1ff, v1
	s_movk_i32 s4, 0x1ff
	v_cmp_lt_u32_e32 vcc, s4, v1
	s_mov_b64 s[6:7], -1
	v_mov_b32_e32 v4, v0
	s_and_saveexec_b64 s[4:5], vcc
	s_cbranch_execz .LBB0_642
	v_readlane_b32 s6, v254, 49
	v_readlane_b32 s7, v254, 50
	s_or_b32 s6, s38, s6
	v_readlane_b32 s12, v254, 35
	v_lshrrev_b32_e32 v1, 9, v1
	s_mulk_i32 s6, 0x1d1
	s_mov_b32 s7, s12
	v_add_u32_e32 v3, 1, v1
	s_lshl_b64 s[6:7], s[6:7], 2
	s_waitcnt lgkmcnt(0)
	s_add_u32 s6, s2, s6
	v_and_b32_e32 v6, 0xfffffe, v3
	v_add_u32_e32 v1, 0x200, v0
	v_mov_b32_e32 v4, 0x9000
	s_addc_u32 s7, s3, s7
	v_lshl_add_u32 v7, v0, 2, v4
	s_mov_b64 s[8:9], 0
	v_mov_b32_e32 v8, v6
	v_mov_b64_e32 v[4:5], v[0:1]
	v_readlane_b32 s13, v254, 36
	v_readlane_b32 s14, v254, 37
	v_readlane_b32 s15, v254, 38

; template <int DK, int DV, int MODE>
; DI void att_gload(const AttArgs& a, int tile, u32x4 (&kr)[(64 * (DK / 8) + NT - 1) / NT], u32x4 (&vr)[(64 * (DV / 8) + NT - 1) / NT]) {
;     ...
; #pragma unroll
;   for (int i = 0; i < NKL; ++i) {
;     const int id = min(t + NT * i, 64 * CK - 1);
;     const int row = id / CK, c = id % CK;
;     if constexpr (MODE == 3) {
;       const bf16_t* src = (c < 8) ? (a.k + (size_t)(kbase + row) * a.ldk + c * 8) : (a.k2 + (size_t)(kbase + row) * a.ldk2 + (c - 8) * 8);
;       kr[i] = *(const u32x4*)src;
;     } else {
;       kr[i] = *(const u32x4*)(a.k + (size_t)(kbase + row) * a.ldk + c * 8);
;     }
;   }
; #pragma unroll
;   for (int i = 0; i < NVL; ++i) {
;     const int id = t + NT * i;
;     const int row = id / CV, c = id % CV;
;     vr[i] = *(const u32x4*)(a.v + (size_t)(kbase + row) * a.ldv + c * 8);
;   }
; template <int DK, int DV, int MODE, int QB, bool PACK = false>
; DI void attn_item(const AttArgs& a, int q0, int t_lo, int t_hi) {
;     ...
;   bf16x8 qf[QB][NKS];
; #pragma unroll
;   for (int qb = 0; qb < QB; ++qb) {
;     const bf16_t* qp = a.q + hg * DK + (size_t)(wq0 + qb * 32 + r) * a.ldq + h * 8;
; #pragma unroll
;     for (int s = 0; s < NKS; ++s) qf[qb][s] = *(const bf16x8*)(qp + s * 16);
;   }
.LBB0_752:
	s_and_b64 vcc, exec, s[0:1]
	s_cbranch_vccz .LBB0_798
	s_mov_b32 s0, 25
	s_ashr_i32 s1, s0, 31
	s_lshl_b64 s[0:1], s[0:1], 3
	s_add_u32 s0, s70, s0
	s_addc_u32 s1, s71, s1
	v_readlane_b32 s0, v255, 60
	v_readlane_b32 s1, v255, 61
	s_nop 4
	s_mul_i32 s3, s20, 0x600
	s_mul_i32 s4, s38, 0xc0
	s_mov_b32 s2, 25
	s_waitcnt lgkmcnt(0)
	s_add_u32 s0, s0, s3
	s_addc_u32 s1, s1, 0
	s_add_u32 s0, s0, s4
	s_addc_u32 s1, s1, 0
	s_ashr_i32 s3, s2, 31
	s_lshl_b64 s[2:3], s[2:3], 3
	s_add_u32 s2, s70, s2
	s_addc_u32 s3, s71, s3
	s_mov_b32 s4, 25
	s_mov_b32 s6, 25
	v_mov_b32_e32 v16, v224
	v_readlane_b32 s2, v255, 60
	v_readlane_b32 s3, v255, 61
	s_nop 4
	v_mov_b32_e32 v209, v2
	v_and_b32_e32 v0, 0xffffffc0, v16
	v_bfe_u32 v17, v16, 5, 1
	v_and_b32_e32 v3, 31, v16
	v_add_u32_e32 v0, s21, v0
	v_lshlrev_b32_e32 v208, 4, v17
	v_or_b32_e32 v206, v0, v3
	v_lshl_add_u64 v[0:1], s[0:1], 0, v[208:209]
	s_mov_b64 s[0:1], 0x8000000
	v_lshl_add_u64 v[0:1], v[0:1], 0, s[0:1]
	s_movk_i32 s5, 0x600
	v_or_b32_e32 v204, 32, v206
	v_mad_i64_i32 v[4:5], s[0:1], v206, s5, v[0:1]
	v_mad_i64_i32 v[0:1], s[0:1], v204, s5, v[0:1]
	global_load_dwordx4 v[188:191], v[4:5], off
	global_load_dwordx4 v[184:187], v[4:5], off offset:32
	global_load_dwordx4 v[180:183], v[4:5], off offset:64
	global_load_dwordx4 v[176:179], v[4:5], off offset:96
	global_load_dwordx4 v[172:175], v[4:5], off offset:128
	global_load_dwordx4 v[168:171], v[4:5], off offset:160
	global_load_dwordx4 v[164:167], v[0:1], off
	global_load_dwordx4 v[160:163], v[0:1], off offset:32
	global_load_dwordx4 v[156:159], v[0:1], off offset:64
	global_load_dwordx4 v[152:155], v[0:1], off offset:96
	global_load_dwordx4 v[148:151], v[0:1], off offset:128
	global_load_dwordx4 v[144:147], v[0:1], off offset:160
	s_lshl_b32 s0, s20, 11
	s_waitcnt lgkmcnt(0)
	s_add_u32 s0, s2, s0
	s_addc_u32 s1, s3, 0
	s_lshl_b32 s2, s38, 8
	s_add_u32 s0, s0, s2
	s_addc_u32 s1, s1, 0
	s_add_u32 s0, s0, 0x9800000
	s_addc_u32 s1, s1, 0
	s_ashr_i32 s5, s4, 31
	s_lshl_b64 s[2:3], s[4:5], 3
	s_add_u32 s2, s70, s2
	s_addc_u32 s3, s71, s3
	s_ashr_i32 s7, s6, 31
	v_mov_b32_e32 v12, v224
	s_lshl_b64 s[4:5], s[6:7], 3
	s_mov_b32 s6, 0x2aaaaaab
	v_min_i32_e32 v0, 0x2ff, v12
	v_mul_hi_i32 v1, v0, s6
	v_lshrrev_b32_e32 v4, 31, v1
	v_ashrrev_i32_e32 v1, 1, v1
	v_add_u32_e32 v4, v1, v4
	v_mul_lo_u32 v1, v4, 12
	s_add_u32 s4, s70, s4
	v_sub_u32_e32 v0, v0, v1
	s_addc_u32 s5, s71, s5
	v_cmp_lt_i32_e32 vcc, 7, v0
	v_ashrrev_i32_e32 v5, 31, v4
	v_lshlrev_b32_e32 v0, 3, v0
	s_and_saveexec_b64 s[6:7], vcc
	s_xor_b64 s[6:7], exec, s[6:7]
	v_lshlrev_b64 v[4:5], 12, v[4:5]
	v_lshl_add_u64 v[4:5], s[30:31], 0, v[4:5]
	v_mov_b32_e32 v1, v2
	v_lshl_add_u64 v[0:1], v[0:1], 1, v[4:5]
	s_mov_b64 s[8:9], 0x280
	v_lshl_add_u64 v[6:7], v[0:1], 0, s[8:9]
	s_or_saveexec_b64 s[6:7], s[6:7]
	v_readlane_b32 s2, v255, 60
	v_readlane_b32 s3, v255, 61
	s_nop 4
	s_nop 0
	v_readlane_b32 s4, v255, 60
	v_readlane_b32 s5, v255, 61
	s_nop 4
	s_xor_b64 exec, exec, s[6:7]
	v_lshlrev_b64 v[4:5], 11, v[4:5]
	v_lshl_add_u64 v[4:5], s[0:1], 0, v[4:5]
	v_ashrrev_i32_e32 v1, 31, v0
	v_lshl_add_u64 v[6:7], v[0:1], 1, v[4:5]
	s_or_b64 exec, exec, s[6:7]
	global_load_dwordx4 v[4:7], v[6:7], off
	v_min_i32_e32 v0, 0xff, v12
	v_add_u32_e32 v0, 0x200, v0
	s_mov_b32 s6, 0x2aaaaaab
	v_mul_hi_i32 v1, v0, s6
	v_lshrrev_b32_e32 v8, 31, v1
	v_ashrrev_i32_e32 v1, 1, v1
	v_add_u32_e32 v10, v1, v8
	v_mul_lo_u32 v1, v10, 12
	v_sub_u32_e32 v0, v0, v1
	v_cmp_lt_i32_e32 vcc, 7, v0
	v_ashrrev_i32_e32 v11, 31, v10
	v_lshlrev_b32_e32 v8, 3, v0
	s_and_saveexec_b64 s[6:7], vcc
	s_xor_b64 s[6:7], exec, s[6:7]
	v_lshlrev_b64 v[0:1], 12, v[10:11]
	v_lshl_add_u64 v[0:1], s[30:31], 0, v[0:1]
	v_mov_b32_e32 v9, v2
	v_lshl_add_u64 v[0:1], v[8:9], 1, v[0:1]
	s_mov_b64 s[8:9], 0x280
	v_lshl_add_u64 v[0:1], v[0:1], 0, s[8:9]
	s_andn2_saveexec_b64 s[6:7], s[6:7]
	v_lshlrev_b64 v[0:1], 11, v[10:11]
	v_lshl_add_u64 v[0:1], s[0:1], 0, v[0:1]
	v_ashrrev_i32_e32 v9, 31, v8
	v_lshl_add_u64 v[0:1], v[8:9], 1, v[0:1]
	s_or_b64 exec, exec, s[6:7]
	s_lshl_b32 s6, s20, 10
	s_lshl_b32 s12, s38, 7
	s_lshl_b32 s13, s6, 1
	s_waitcnt lgkmcnt(0)
	s_add_u32 s2, s2, s13
	global_load_dwordx4 v[8:11], v[0:1], off
	v_ashrrev_i32_e32 v0, 31, v12
	s_addc_u32 s3, s3, 0
	s_lshl_b32 s6, s12, 1
	v_lshrrev_b32_e32 v0, 29, v0
	s_add_u32 s2, s2, s6
	v_add_u32_e32 v1, v12, v0
	s_addc_u32 s3, s3, 0
	v_ashrrev_i32_e32 v0, 3, v1
	v_and_b32_e32 v1, 0x1ffffff8, v1
	s_add_u32 s2, s2, 0x9800080
	v_sub_u32_e32 v12, v12, v1
	v_ashrrev_i32_e32 v1, 31, v0
	s_addc_u32 s3, s3, 0
	v_lshlrev_b32_e32 v12, 3, v12
	v_lshlrev_b64 v[0:1], 11, v[0:1]
	v_ashrrev_i32_e32 v13, 31, v12
	v_lshl_add_u64 v[0:1], s[2:3], 0, v[0:1]
	v_lshl_add_u64 v[0:1], v[12:13], 1, v[0:1]
	global_load_dwordx4 v[12:15], v[0:1], off
	v_mov_b32_e32 v0, v224
	s_movk_i32 s6, 0x300
	s_nop 0
	v_cmp_gt_i32_e32 vcc, s6, v0
	s_and_saveexec_b64 s[6:7], vcc
	s_cbranch_execz .LBB0_763
	s_mov_b32 s8, 0x2aaaaaab
	v_mul_hi_i32 v1, v0, s8
	v_lshrrev_b32_e32 v18, 31, v1
	v_ashrrev_i32_e32 v1, 1, v1
	v_add_u32_e32 v1, v1, v18
	v_mul_lo_u32 v18, v1, 12
	s_movk_i32 s8, 0xd0
	v_sub_u32_e32 v18, v0, v18
	v_mul_lo_u32 v1, v1, s8
	v_lshl_add_u32 v1, v18, 4, v1
	s_waitcnt vmcnt(2)
	ds_write_b128 v1, v[4:7]

; template <int DK, int DV, int MODE>
; DI void att_gload(const AttArgs& a, int tile, u32x4 (&kr)[(64 * (DK / 8) + NT - 1) / NT], u32x4 (&vr)[(64 * (DV / 8) + NT - 1) / NT]) {
;     ...
; #pragma unroll
;   for (int i = 0; i < NKL; ++i) {
;     const int id = min(t + NT * i, 64 * CK - 1);
;     const int row = id / CK, c = id % CK;
;     if constexpr (MODE == 3) {
;       const bf16_t* src = (c < 8) ? (a.k + (size_t)(kbase + row) * a.ldk + c * 8) : (a.k2 + (size_t)(kbase + row) * a.ldk2 + (c - 8) * 8);
;       kr[i] = *(const u32x4*)src;
;     } else {
;       kr[i] = *(const u32x4*)(a.k + (size_t)(kbase + row) * a.ldk + c * 8);
;     }
;   }
; #pragma unroll
;   for (int i = 0; i < NVL; ++i) {
;     const int id = t + NT * i;
;     const int row = id / CV, c = id % CV;
;     vr[i] = *(const u32x4*)(a.v + (size_t)(kbase + row) * a.ldv + c * 8);
;   }
; __global__ void __launch_bounds__(512, 2) mega(Params p) {
;     ...
;           const int qtb = rest & 15, pgb = rest >> 4;
;           const int pairb = pgb * 8 + pl;
;           const int bb = pairb >> 1, kvb = pairb & 1;
;           const bf16_t* zrb = G_ZB + (size_t)bb * SEQ * ZLD;
;           a.q = zrb + 768 + kvb * 256; a.k = zrb + 1280 + kvb * 64; a.v = zrb + 1408 + kvb * 64;
;           a.o = G_OB + (size_t)bb * SEQ * DM + 512 + kvb * 256;
;           a.sinkp = inp(6) + j * 8 + kvb * 4;
;           const int q0b = qtb * 128;
;           const int tlo = max(q0b - 128, 0) >> 6, thi = min(q0b + 128 + 128, SEQ) >> 6;
;           attn_item<64, 64, 1, 2, true>(a, q0b, tlo, thi);
.LBB0_799:
	s_andn2_b64 vcc, exec, s[0:1]
	s_cbranch_vccnz .LBB0_634
	s_lshr_b32 s0, s25, 4
	s_and_b32 s0, s0, 8
	s_or_b32 s0, s0, s38
	s_and_b32 s13, s25, 1
	s_lshl_b32 s0, s0, 21
	s_bfe_u32 s15, s25, 0x40003
	s_lshl_b32 s14, s13, 2
	s_and_b32 s12, s0, 0x1c00000
	s_mov_b32 s8, 25
	s_cmpk_gt_i32 s25, 0xff
	s_mov_b64 s[0:1], -1
	s_cbranch_scc0 .LBB0_829
	s_mov_b32 s0, 25
	s_ashr_i32 s1, s0, 31
	s_lshl_b64 s[0:1], s[0:1], 3
	s_add_u32 s0, s70, s0
	s_addc_u32 s1, s71, s1
	v_readlane_b32 s0, v255, 60
	v_readlane_b32 s1, v255, 61
	s_nop 4
	s_lshl_b32 s3, s12, 1
	s_mov_b32 s2, 25
	v_mov_b32_e32 v3, v224
	s_waitcnt lgkmcnt(0)
	s_add_u32 s0, s0, s3
	s_addc_u32 s1, s1, 0
	s_add_u32 s0, s0, 0x2000000
	s_addc_u32 s1, s1, 0
	s_lshl_b32 s3, s13, 9
	s_add_u32 s4, s0, s3
	s_addc_u32 s5, s1, 0
	s_lshl_b32 s3, s13, 7
	s_add_u32 s30, s0, s3
	s_addc_u32 s31, s1, 0
	s_ashr_i32 s3, s2, 31
	s_lshl_b64 s[0:1], s[2:3], 3
	s_add_u32 s0, s70, s0
	s_mov_b32 s2, 6
	s_addc_u32 s1, s71, s1
	s_ashr_i32 s3, s2, 31
	s_lshl_b64 s[2:3], s[2:3], 3
	s_add_u32 s2, s70, s2
	s_addc_u32 s3, s71, s3
	s_lshl_b32 s6, s15, 7
	v_mov_b32_e32 v0, 0x80
	v_sub_u32_e64 v5, s6, v0 clamp
	v_ashrrev_i32_e32 v186, 7, v3
	v_and_b32_e32 v0, 64, v3
	v_lshlrev_b32_e32 v184, 6, v186
	v_bfe_u32 v187, v3, 5, 1
	v_and_b32_e32 v1, 31, v3
	v_or_b32_e32 v4, s6, v0
	v_ashrrev_i32_e32 v185, 31, v184
	v_lshl_add_u64 v[6:7], v[184:185], 1, s[4:5]
	v_or_b32_e32 v213, v4, v1
	v_lshlrev_b32_e32 v188, 4, v187
	v_mov_b32_e32 v189, v2
	v_lshl_add_u64 v[6:7], v[6:7], 0, v[188:189]
	v_lshlrev_b32_e32 v8, 12, v213
	v_mov_b32_e32 v9, v2
	v_lshl_add_u64 v[8:9], v[6:7], 0, v[8:9]
	v_or_b32_e32 v189, 32, v213
	global_load_dwordx4 v[144:147], v[8:9], off offset:1536
	global_load_dwordx4 v[148:151], v[8:9], off offset:1568
	global_load_dwordx4 v[152:155], v[8:9], off offset:1600
	global_load_dwordx4 v[156:159], v[8:9], off offset:1632
	v_lshlrev_b32_e32 v8, 12, v189
	v_mov_b32_e32 v9, v2
	v_lshl_add_u64 v[6:7], v[6:7], 0, v[8:9]
	v_mov_b32_e32 v10, v224
	global_load_dwordx4 v[160:163], v[6:7], off offset:1536
	global_load_dwordx4 v[164:167], v[6:7], off offset:1568
	global_load_dwordx4 v[168:171], v[6:7], off offset:1600
	global_load_dwordx4 v[172:175], v[6:7], off offset:1632
	s_movk_i32 s4, 0x1ff
	v_min_i32_e32 v6, 0x1ff, v10
	v_ashrrev_i32_e32 v7, 31, v6
	v_lshrrev_b32_e32 v7, 29, v7
	v_add_u32_e32 v7, v6, v7
	v_ashrrev_i32_e32 v8, 3, v7
	v_and_b32_e32 v7, 0x1ffffff8, v7
	v_sub_u32_e32 v9, v6, v7
	v_add_u32_e32 v6, v8, v5
	v_ashrrev_i32_e32 v7, 31, v6
	v_lshlrev_b32_e32 v8, 3, v9
	v_lshlrev_b64 v[6:7], 12, v[6:7]
	v_ashrrev_i32_e32 v9, 31, v8
	v_lshl_add_u64 v[6:7], s[30:31], 0, v[6:7]
	v_lshl_add_u64 v[6:7], v[8:9], 1, v[6:7]
	v_ashrrev_i32_e32 v8, 31, v10
	v_lshrrev_b32_e32 v8, 29, v8
	v_add_u32_e32 v8, v10, v8
	v_ashrrev_i32_e32 v9, 3, v8
	v_and_b32_e32 v8, 0x1ffffff8, v8
	v_sub_u32_e32 v10, v10, v8
	v_add_u32_e32 v8, v9, v5
	v_ashrrev_i32_e32 v9, 31, v8
	v_lshlrev_b32_e32 v10, 3, v10
	v_lshlrev_b64 v[8:9], 12, v[8:9]
	v_ashrrev_i32_e32 v11, 31, v10
	v_lshl_add_u64 v[8:9], s[30:31], 0, v[8:9]
	v_lshl_add_u64 v[8:9], v[10:11], 1, v[8:9]
	global_load_dwordx4 v[176:179], v[6:7], off offset:2560
	global_load_dwordx4 v[180:183], v[8:9], off offset:2816
	v_mov_b32_e32 v6, v224
	s_mov_b32 s72, s25
	s_mov_b32 s33, s24
	v_readfirstlane_b32 s7, v5
	s_nop 0
	v_cmp_lt_i32_e32 vcc, s4, v6
	s_and_saveexec_b64 s[4:5], vcc
	s_xor_b64 s[4:5], exec, s[4:5]
	v_lshrrev_b32_e32 v5, 3, v6
	s_movk_i32 s9, 0x90
	v_lshlrev_b32_e32 v6, 4, v6
	v_mul_lo_u32 v5, v5, s9
	v_and_b32_e32 v7, 0x70, v6
	s_or_saveexec_b64 s[4:5], s[4:5]
	v_readlane_b32 s68, v255, 60
	v_readlane_b32 s69, v255, 61
	s_nop 4
	s_load_dwordx2 s[66:67], s[2:3], 0x0
	s_xor_b64 exec, exec, s[4:5]
	s_cbranch_execz .LBB0_805
	v_ashrrev_i32_e32 v5, 31, v6
	v_lshrrev_b32_e32 v5, 29, v5
	v_add_u32_e32 v7, v6, v5
	v_lshrrev_b32_e32 v5, 3, v7
	v_and_b32_e32 v7, 0xffffff8, v7
	s_movk_i32 s0, 0x90
	v_sub_u32_e32 v6, v6, v7
	v_mul_lo_u32 v5, v5, s0
	v_lshlrev_b32_e32 v7, 4, v6
	v_add_u32_e32 v6, v5, v7
	s_waitcnt vmcnt(1)
	ds_write_b128 v6, v[176:179]

; #define BAR8 __builtin_amdgcn_s_barrier()
; #define G_XF (outp())
; #define G_SS ((float*)(wsp() + OFF_SS))
;     ...
;   const int brow = m0, bcol = n0;
;   const int wid = t >> 6, lane = t & 63, wr = wid >> 2, wc = wid & 3, fr = lane & 15, fq = lane >> 4;
;   f32x4 acc[2][2][4][2];
;   {
;     float zinit = 0.f;
;     asm volatile("" : "+v"(zinit));
; #pragma unroll
;     for (int a = 0; a < 2; ++a)
; #pragma unroll
;       for (int b = 0; b < 2; ++b)
; #pragma unroll
;         for (int m = 0; m < 4; ++m)
; #pragma unroll
;           for (int n = 0; n < 2; ++n)
; #pragma unroll
;             for (int j = 0; j < 4; ++j) acc[a][b][m][n][j] = zinit;
;   }
;   bf16x8 At[4][2], B0[2][2], B1[2][2];
;   const int nt = K / 64;
;   if (!pre) {
;     STAGE8(SB8(0, 0), Bt, K, bcol, 0); STAGE8(SA8(0, 0), A, lda, brow, 0);
;     STAGE8(SB8(0, 1), Bt, K, bcol + 128, 0); STAGE8(SA8(0, 1), A, lda, brow + 128, 0);
;   }
;   if (wr == 1) BAR8;
; __global__ void __launch_bounds__(512, 2) mega(Params p) {
;     ...
;     for (int item = bid; item < 4 * 64; item += nb) {
;       const int nt = item >> 6, mt = item & 63;
;       e.ss = nullptr; e.xf = G_XF; e.xb = G_XB; e.ss_out = G_SS;
;       gemm_tile<EPI_RESID, 256, false>(G_OB, DM, wb + W_OUT, DM, mt * 256, nt * 256, e);
.LBB0_905:
	s_mov_b32 s0, 24
	s_mov_b32 s0, 25
	s_ashr_i32 s1, s0, 31
	s_lshl_b64 s[0:1], s[0:1], 3
	s_add_u32 s0, s70, s0
	s_addc_u32 s1, s71, s1
	v_readlane_b32 s6, v255, 60
	v_readlane_b32 s7, v255, 61
	s_nop 4
	s_mov_b32 s0, 25
	s_ashr_i32 s1, s0, 31
	s_lshl_b64 s[0:1], s[0:1], 3
	s_add_u32 s0, s70, s0
	s_addc_u32 s1, s71, s1
	s_mov_b32 s2, 25
	v_readlane_b32 s0, v255, 60
	v_readlane_b32 s1, v255, 61
	s_nop 4
	s_ashr_i32 s3, s2, 31
	s_lshl_b64 s[2:3], s[2:3], 3
	s_add_u32 s2, s70, s2
	s_addc_u32 s3, s71, s3
	v_mov_b32_e32 v3, v224
	v_readlane_b32 s2, v255, 60
	v_readlane_b32 s3, v255, 61
	s_nop 4
	v_mov_b32_e32 v18, 1
	v_bfe_i32 v1, v3, 27, 1
	s_waitcnt vmcnt(10)
	v_lshlrev_b32_e32 v150, 4, v3
	v_lshrrev_b32_e32 v1, 22, v1
	v_add_u32_e32 v1, v150, v1
	v_and_b32_e32 v1, 0xfffffc00, v1
	v_ashrrev_i32_e32 v0, 31, v3
	v_sub_u32_e32 v1, v150, v1
	v_lshrrev_b32_e32 v0, 26, v0
	v_lshrrev_b32_e32 v5, 4, v1
	v_add_u32_e32 v0, v3, v0
	v_bitop3_b32 v5, v5, v1, 32 bitop3:0x6c
	v_ashrrev_i32_e32 v1, 31, v1
	s_waitcnt lgkmcnt(0)
	s_add_u32 s29, s2, 0x6000000
	v_ashrrev_i32_e32 v0, 6, v0
	v_lshrrev_b32_e32 v1, 26, v1
	s_addc_u32 s33, s3, 0
	s_lshl_b32 s8, s24, 8
	v_lshlrev_b32_e32 v6, 3, v0
	v_add_u32_e32 v1, v5, v1
	s_and_b32 s25, s8, 0x3f00
	s_lshl_b32 s8, s24, 2
	v_and_b32_e32 v6, -16, v6
	v_ashrrev_i32_e32 v1, 6, v1
	s_and_b32 s8, s8, 0xffffff00
	v_add_u32_e32 v16, v1, v6
	v_mul_i32_i24_e32 v1, 64, v1
	s_ashr_i32 s9, s8, 31
	v_lshlrev_b32_e32 v0, 5, v0
	v_sub_u32_e32 v1, v5, v1
	s_waitcnt vmcnt(9)
	v_add_u32_e32 v152, 0x2000, v150
	s_lshl_b64 s[12:13], s[8:9], 11
	v_and_b32_e32 v0, 32, v0
	v_ashrrev_i16_sdwa v1, v18, sext(v1) dst_sel:DWORD dst_unused:UNUSED_PAD src0_sel:DWORD src1_sel:BYTE_0
	v_ashrrev_i32_e32 v5, 31, v152
	s_add_u32 s12, s14, s12
	v_add_u32_sdwa v0, v0, sext(v1) dst_sel:DWORD dst_unused:UNUSED_PAD src0_sel:DWORD src1_sel:WORD_0
	v_ashrrev_i32_e32 v17, 31, v16
	v_lshrrev_b32_e32 v5, 22, v5
	s_addc_u32 s13, s15, s13
	v_lshlrev_b64 v[6:7], 11, v[16:17]
	v_ashrrev_i32_e32 v1, 31, v0
	v_add_u32_e32 v5, v152, v5
	v_lshl_add_u64 v[10:11], s[12:13], 0, v[6:7]
	v_lshlrev_b64 v[8:9], 1, v[0:1]
	v_ashrrev_i32_e32 v5, 10, v5
	v_lshl_add_u64 v[14:15], v[10:11], 0, v[8:9]
	v_mul_i32_i24_e32 v10, 0x400, v5
	v_sub_u32_e32 v10, v152, v10
	v_lshrrev_b32_e32 v11, 4, v10
	v_bitop3_b32 v10, v11, v10, 32 bitop3:0x6c
	v_ashrrev_i32_e32 v12, 31, v10
	v_lshrrev_b32_e32 v12, 26, v12
	v_lshlrev_b32_e32 v11, 3, v5
	v_add_u32_e32 v12, v10, v12
	v_and_b32_e32 v11, -16, v11
	v_ashrrev_i32_e32 v13, 6, v12
	v_add_u32_e32 v24, v13, v11
	v_and_b32_e32 v11, 0xc0, v12
	v_lshlrev_b32_e32 v5, 5, v5
	v_sub_u32_e32 v10, v10, v11
	v_add_u32_e32 v151, 0x10000, v150
	v_and_b32_e32 v5, 32, v5
	v_ashrrev_i16_sdwa v10, v18, sext(v10) dst_sel:DWORD dst_unused:UNUSED_PAD src0_sel:DWORD src1_sel:BYTE_0
	v_ashrrev_i32_e32 v25, 31, v24
	v_readfirstlane_b32 s27, v151
	v_add_u32_sdwa v132, v5, sext(v10) dst_sel:DWORD dst_unused:UNUSED_PAD src0_sel:DWORD src1_sel:WORD_0
	v_lshlrev_b64 v[10:11], 11, v[24:25]
	s_waitcnt vmcnt(8)
	v_add_u32_e32 v157, 0x12000, v150
	v_mov_b32_e32 v4, v2
	s_mov_b32 m0, s27
	v_lshl_add_u64 v[18:19], s[12:13], 0, v[10:11]
	v_readfirstlane_b32 s12, v157
	global_load_lds_dwordx4 v[14:15], off
	v_ashrrev_i32_e32 v133, 31, v132
	s_mov_b32 m0, s12
	s_lshl_b32 s27, s25, 10
	s_lshl_b32 s12, s25, 11
	v_lshlrev_b64 v[12:13], 1, v[132:133]
	s_add_u32 s12, s29, s12
	v_lshl_add_u64 v[18:19], v[18:19], 0, v[12:13]
	s_addc_u32 s13, s33, 0
	v_readfirstlane_b32 s30, v150
	global_load_lds_dwordx4 v[18:19], off
	v_lshl_add_u64 v[20:21], s[12:13], 0, v[6:7]
	s_mov_b32 m0, s30
	s_or_b32 s30, s8, 0x80
	v_lshl_add_u64 v[20:21], v[20:21], 0, v[8:9]
	v_lshl_add_u64 v[22:23], s[12:13], 0, v[10:11]
	v_readfirstlane_b32 s12, v152
	s_ashr_i32 s31, s30, 31
	global_load_lds_dwordx4 v[20:21], off
	s_mov_b32 m0, s12
	s_lshl_b64 s[12:13], s[30:31], 11
	s_add_u32 s12, s14, s12
	s_addc_u32 s13, s15, s13
	v_add_u32_e32 v159, 0x14000, v150
	v_lshl_add_u64 v[22:23], v[22:23], 0, v[12:13]
	v_lshl_add_u64 v[26:27], s[12:13], 0, v[6:7]
	v_readfirstlane_b32 s31, v159
	v_add_u32_e32 v161, 0x16000, v150
	s_bitset1_b32 s27, 17
	global_load_lds_dwordx4 v[22:23], off
	v_lshl_add_u64 v[26:27], v[26:27], 0, v[8:9]
	s_mov_b32 m0, s31
	v_lshl_add_u64 v[28:29], s[12:13], 0, v[10:11]
	v_readfirstlane_b32 s12, v161
	s_lshl_b32 s27, s27, 1
	global_load_lds_dwordx4 v[26:27], off
	s_mov_b32 m0, s12
	s_add_u32 s12, s29, s27
	s_addc_u32 s13, s33, 0
	v_add_u32_e32 v162, 0x4000, v150
	v_lshl_add_u64 v[28:29], v[28:29], 0, v[12:13]
	v_lshl_add_u64 v[30:31], s[12:13], 0, v[6:7]
	v_readfirstlane_b32 s29, v162
	global_load_lds_dwordx4 v[28:29], off
	v_lshl_add_u64 v[30:31], v[30:31], 0, v[8:9]
	s_mov_b32 m0, s29
	v_add_u32_e32 v163, 0x6000, v150
	global_load_lds_dwordx4 v[30:31], off
	v_lshl_add_u64 v[30:31], s[12:13], 0, v[10:11]
	v_readfirstlane_b32 s12, v163
	v_lshl_add_u64 v[30:31], v[30:31], 0, v[12:13]
	s_mov_b32 m0, s12
	v_ashrrev_i32_e32 v5, 8, v3
	global_load_lds_dwordx4 v[30:31], off
	v_cmp_eq_u32_e32 vcc, 1, v5
	s_and_saveexec_b64 s[12:13], vcc
	s_cbranch_execz .LBB0_907
	s_barrier

; #define BAR8 __builtin_amdgcn_s_barrier()
; #define G_SS ((float*)(wsp() + OFF_SS))
; #define G_SSMEM ((float*)(wsp() + OFF_SSMEM))
;     ...
;     STAGE8(SB8(0, 0), Bt, K, bcol, 0); STAGE8(SA8(0, 0), A, lda, brow, 0);
;     STAGE8(SB8(0, 1), Bt, K, bcol + 128, 0); STAGE8(SA8(0, 1), A, lda, brow + 128, 0);
;   }
;   if (wr == 1) BAR8;
; __global__ void __launch_bounds__(512, 2) mega(Params p) {
;     ...
;     for (int item = bid; item < 2 * 64 + 4 * 8; item += nb) {
;       if (item < 128) {
;         const int nt = item >> 6, mt = item & 63;
;         e.ss = G_SS; e.nss = 16; e.inv_n = 1.f / 1024.f; e.out = G_XQ; e.ldo = 512;
;         gemm_tile<EPI_PLAIN, 256, true>(G_XB, DM, wb + W_XQ, DM, mt * 256, nt * 256, e);
;       } else {
;         const int it = item - 128;
;         const int nt = it >> 3, mt = it & 7;
;         e.ss = G_SSMEM; e.nss = 1; e.inv_n = 1.f / 1024.f; e.out = G_MEMKV; e.ldo = 1024;
;         gemm_tile<EPI_PLAIN, 256, false>(G_MEMB, DM, wb + W_XKV, DM, mt * 256, nt * 256, e);
;       }
.LBB0_1001:
	s_lshr_b32 s27, s37, 8
	s_cmpk_gt_i32 s38, 0x7f
	s_mov_b64 s[0:1], -1
	s_cbranch_scc0 .LBB0_1011
	s_mov_b32 s0, 25
	s_ashr_i32 s1, s0, 31
	s_lshl_b64 s[0:1], s[0:1], 3
	s_add_u32 s0, s70, s0
	s_addc_u32 s1, s71, s1
	v_readlane_b32 s6, v255, 60
	v_readlane_b32 s7, v255, 61
	s_nop 4
	s_mov_b32 s0, 25
	s_ashr_i32 s1, s0, 31
	s_lshl_b64 s[0:1], s[0:1], 3
	s_add_u32 s0, s70, s0
	s_addc_u32 s1, s71, s1
	v_readlane_b32 s2, v255, 60
	v_readlane_b32 s3, v255, 61
	s_nop 4
	s_mov_b32 s0, 25
	s_ashr_i32 s1, s0, 31
	s_lshl_b64 s[0:1], s[0:1], 3
	s_add_u32 s0, s70, s0
	s_addc_u32 s1, s71, s1
	v_mov_b32_e32 v3, v224
	v_readlane_b32 s12, v255, 60
	v_readlane_b32 s13, v255, 61
	s_nop 4
	s_lshl_b32 s0, s38, 8
	v_bfe_i32 v1, v3, 27, 1
	s_waitcnt vmcnt(10)
	v_lshlrev_b32_e32 v150, 4, v3
	v_lshrrev_b32_e32 v1, 22, v1
	v_add_u32_e32 v1, v150, v1
	v_and_b32_e32 v1, 0xfffffc00, v1
	v_ashrrev_i32_e32 v0, 31, v3
	v_sub_u32_e32 v1, v150, v1
	v_lshrrev_b32_e32 v0, 26, v0
	v_lshrrev_b32_e32 v5, 4, v1
	v_add_u32_e32 v0, v3, v0
	v_bitop3_b32 v5, v5, v1, 32 bitop3:0x6c
	v_ashrrev_i32_e32 v1, 31, v1
	v_ashrrev_i32_e32 v0, 6, v0
	v_lshrrev_b32_e32 v1, 26, v1
	v_lshlrev_b32_e32 v6, 3, v0
	v_add_u32_e32 v1, v5, v1
	s_and_b32 s29, s0, 0x700
	s_lshl_b32 s0, s38, 5
	v_and_b32_e32 v6, -16, v6
	v_ashrrev_i32_e32 v1, 6, v1
	s_and_b32 s39, s0, 0x7fffff00
	v_add_u32_e32 v6, v1, v6
	v_mul_i32_i24_e32 v1, 64, v1
	s_add_i32 s0, s39, 0xfffff000
	v_lshlrev_b32_e32 v0, 5, v0
	v_sub_u32_e32 v1, v5, v1
	v_mov_b32_e32 v14, 1
	s_waitcnt vmcnt(9)
	v_add_u32_e32 v152, 0x2000, v150
	s_lshl_b32 s1, s0, 11
	v_and_b32_e32 v0, 32, v0
	v_ashrrev_i16_sdwa v1, v14, sext(v1) dst_sel:DWORD dst_unused:UNUSED_PAD src0_sel:DWORD src1_sel:BYTE_0
	v_ashrrev_i32_e32 v5, 31, v152
	s_add_u32 s14, s24, s1
	v_add_u32_sdwa v0, v0, sext(v1) dst_sel:DWORD dst_unused:UNUSED_PAD src0_sel:DWORD src1_sel:WORD_0
	v_ashrrev_i32_e32 v7, 31, v6
	v_lshrrev_b32_e32 v5, 22, v5
	s_addc_u32 s15, s25, 0
	v_lshlrev_b64 v[132:133], 11, v[6:7]
	v_ashrrev_i32_e32 v1, 31, v0
	v_add_u32_e32 v5, v152, v5
	v_lshl_add_u64 v[8:9], s[14:15], 0, v[132:133]
	v_lshlrev_b64 v[6:7], 1, v[0:1]
	v_ashrrev_i32_e32 v5, 10, v5
	v_lshl_add_u64 v[10:11], v[8:9], 0, v[6:7]
	v_mul_i32_i24_e32 v8, 0x400, v5
	v_sub_u32_e32 v8, v152, v8
	v_lshrrev_b32_e32 v9, 4, v8
	v_bitop3_b32 v9, v9, v8, 32 bitop3:0x6c
	v_ashrrev_i32_e32 v12, 31, v9
	v_add_u32_e32 v151, 0x10000, v150
	v_lshrrev_b32_e32 v12, 26, v12
	v_readfirstlane_b32 s1, v151
	v_add_u32_e32 v12, v9, v12
	s_waitcnt vmcnt(8)
	v_add_u32_e32 v157, 0x12000, v150
	v_mov_b32_e32 v4, v2
	s_mov_b32 m0, s1
	v_lshlrev_b32_e32 v8, 3, v5
	v_ashrrev_i32_e32 v13, 6, v12
	v_and_b32_e32 v12, 0xc0, v12
	v_readfirstlane_b32 s1, v157
	global_load_lds_dwordx4 v[10:11], off
	v_and_b32_e32 v8, -16, v8
	v_lshlrev_b32_e32 v5, 5, v5
	v_sub_u32_e32 v9, v9, v12
	s_mov_b32 m0, s1
	s_lshl_b32 s1, s29, 11
	v_add_u32_e32 v8, v13, v8
	v_and_b32_e32 v5, 32, v5
	v_ashrrev_i16_sdwa v9, v14, sext(v9) dst_sel:DWORD dst_unused:UNUSED_PAD src0_sel:DWORD src1_sel:BYTE_0
	s_waitcnt lgkmcnt(0)
	s_add_u32 s1, s12, s1
	v_add_u32_sdwa v134, v5, sext(v9) dst_sel:DWORD dst_unused:UNUSED_PAD src0_sel:DWORD src1_sel:WORD_0
	v_ashrrev_i32_e32 v9, 31, v8
	s_addc_u32 s40, s13, 0
	v_lshlrev_b64 v[136:137], 11, v[8:9]
	v_ashrrev_i32_e32 v135, 31, v134
	s_add_u32 s8, s1, 0xb800000
	v_lshl_add_u64 v[12:13], s[14:15], 0, v[136:137]
	v_lshlrev_b64 v[8:9], 1, v[134:135]
	s_addc_u32 s9, s40, 0
	v_lshl_add_u64 v[12:13], v[12:13], 0, v[8:9]
	v_lshl_add_u64 v[14:15], s[8:9], 0, v[132:133]
	v_readfirstlane_b32 s20, v150
	global_load_lds_dwordx4 v[12:13], off
	v_lshl_add_u64 v[16:17], v[14:15], 0, v[6:7]
	s_mov_b32 m0, s20
	v_readfirstlane_b32 s20, v152
	global_load_lds_dwordx4 v[16:17], off
	s_mov_b32 m0, s20
	s_add_u32 s20, s14, 0x40000
	v_lshl_add_u64 v[14:15], s[8:9], 0, v[136:137]
	s_addc_u32 s21, s15, 0
	v_add_u32_e32 v159, 0x14000, v150
	v_lshl_add_u64 v[14:15], v[14:15], 0, v[8:9]
	v_lshl_add_u64 v[18:19], s[20:21], 0, v[132:133]
	v_readfirstlane_b32 s41, v159
	global_load_lds_dwordx4 v[14:15], off
	v_lshl_add_u64 v[18:19], v[18:19], 0, v[6:7]
	s_mov_b32 m0, s41
	v_add_u32_e32 v160, 0x16000, v150
	global_load_lds_dwordx4 v[18:19], off
	v_lshl_add_u64 v[18:19], s[20:21], 0, v[136:137]
	v_readfirstlane_b32 s20, v160
	s_mov_b32 m0, s20
	s_add_u32 s20, s1, 0xb840000
	v_lshl_add_u64 v[18:19], v[18:19], 0, v[8:9]
	s_addc_u32 s21, s40, 0
	v_add_u32_e32 v162, 0x4000, v150
	global_load_lds_dwordx4 v[18:19], off
	v_lshl_add_u64 v[18:19], s[20:21], 0, v[132:133]
	v_readfirstlane_b32 s1, v162
	v_lshl_add_u64 v[18:19], v[18:19], 0, v[6:7]
	s_mov_b32 m0, s1
	v_add_u32_e32 v163, 0x6000, v150
	global_load_lds_dwordx4 v[18:19], off
	v_lshl_add_u64 v[18:19], s[20:21], 0, v[136:137]
	v_readfirstlane_b32 s1, v163
	v_lshl_add_u64 v[18:19], v[18:19], 0, v[8:9]
	s_mov_b32 m0, s1
	v_ashrrev_i32_e32 v5, 8, v3
	global_load_lds_dwordx4 v[18:19], off
	v_cmp_eq_u32_e32 vcc, 1, v5
	s_and_saveexec_b64 s[20:21], vcc
	s_cbranch_execz .LBB0_1004
	s_barrier

; #define BAR8 __builtin_amdgcn_s_barrier()
; #define G_SS ((float*)(wsp() + OFF_SS))
;     ...
;     STAGE8(SB8(0, 0), Bt, K, bcol, 0); STAGE8(SA8(0, 0), A, lda, brow, 0);
;     STAGE8(SB8(0, 1), Bt, K, bcol + 128, 0); STAGE8(SA8(0, 1), A, lda, brow + 128, 0);
;   }
;   if (wr == 1) BAR8;
; __global__ void __launch_bounds__(512, 2) mega(Params p) {
;     ...
;       if (item < 128) {
;         const int nt = item >> 6, mt = item & 63;
;         e.ss = G_SS; e.nss = 16; e.inv_n = 1.f / 1024.f; e.out = G_XQ; e.ldo = 512;
;         gemm_tile<EPI_PLAIN, 256, true>(G_XB, DM, wb + W_XQ, DM, mt * 256, nt * 256, e);
.LBB0_1011:
	s_and_b64 vcc, exec, s[0:1]
	s_cbranch_vccz .LBB0_1000
	s_mov_b32 s0, 25
	s_ashr_i32 s1, s0, 31
	s_lshl_b64 s[0:1], s[0:1], 3
	s_add_u32 s0, s70, s0
	s_addc_u32 s1, s71, s1
	v_readlane_b32 s6, v255, 60
	v_readlane_b32 s7, v255, 61
	s_nop 4
	s_mov_b32 s0, 25
	s_ashr_i32 s1, s0, 31
	s_lshl_b64 s[0:1], s[0:1], 3
	s_add_u32 s0, s70, s0
	s_addc_u32 s1, s71, s1
	v_readlane_b32 s2, v255, 60
	v_readlane_b32 s3, v255, 61
	s_nop 4
	s_mov_b32 s0, 25
	s_ashr_i32 s1, s0, 31
	s_lshl_b64 s[0:1], s[0:1], 3
	s_add_u32 s0, s70, s0
	s_addc_u32 s1, s71, s1
	v_mov_b32_e32 v3, v224
	v_readlane_b32 s12, v255, 60
	v_readlane_b32 s13, v255, 61
	s_nop 4
	s_lshl_b32 s0, s38, 8
	v_bfe_i32 v1, v3, 27, 1
	s_waitcnt vmcnt(10)
	v_lshlrev_b32_e32 v150, 4, v3
	v_lshrrev_b32_e32 v1, 22, v1
	v_add_u32_e32 v1, v150, v1
	v_and_b32_e32 v1, 0xfffffc00, v1
	v_ashrrev_i32_e32 v0, 31, v3
	v_sub_u32_e32 v1, v150, v1
	v_lshrrev_b32_e32 v0, 26, v0
	v_lshrrev_b32_e32 v5, 4, v1
	v_add_u32_e32 v0, v3, v0
	v_bitop3_b32 v5, v5, v1, 32 bitop3:0x6c
	v_ashrrev_i32_e32 v1, 31, v1
	v_ashrrev_i32_e32 v0, 6, v0
	v_lshrrev_b32_e32 v1, 26, v1
	v_lshlrev_b32_e32 v6, 3, v0
	v_add_u32_e32 v1, v5, v1
	s_and_b32 s20, s0, 0x3f00
	s_lshl_b32 s0, s38, 2
	v_and_b32_e32 v6, -16, v6
	v_ashrrev_i32_e32 v1, 6, v1
	s_and_b32 s0, s0, 0xffffff00
	v_add_u32_e32 v6, v1, v6
	v_mul_i32_i24_e32 v1, 64, v1
	s_ashr_i32 s1, s0, 31
	v_lshlrev_b32_e32 v0, 5, v0
	v_sub_u32_e32 v1, v5, v1
	v_mov_b32_e32 v14, 1
	s_waitcnt vmcnt(9)
	v_add_u32_e32 v152, 0x2000, v150
	s_lshl_b64 s[8:9], s[0:1], 11
	v_and_b32_e32 v0, 32, v0
	v_ashrrev_i16_sdwa v1, v14, sext(v1) dst_sel:DWORD dst_unused:UNUSED_PAD src0_sel:DWORD src1_sel:BYTE_0
	v_ashrrev_i32_e32 v5, 31, v152
	s_add_u32 s8, s30, s8
	v_add_u32_sdwa v0, v0, sext(v1) dst_sel:DWORD dst_unused:UNUSED_PAD src0_sel:DWORD src1_sel:WORD_0
	v_ashrrev_i32_e32 v7, 31, v6
	v_lshrrev_b32_e32 v5, 22, v5
	s_addc_u32 s9, s31, s9
	v_lshlrev_b64 v[132:133], 11, v[6:7]
	v_ashrrev_i32_e32 v1, 31, v0
	v_add_u32_e32 v5, v152, v5
	v_lshl_add_u64 v[8:9], s[8:9], 0, v[132:133]
	v_lshlrev_b64 v[6:7], 1, v[0:1]
	v_ashrrev_i32_e32 v5, 10, v5
	v_lshl_add_u64 v[10:11], v[8:9], 0, v[6:7]
	v_mul_i32_i24_e32 v8, 0x400, v5
	v_sub_u32_e32 v8, v152, v8
	v_lshrrev_b32_e32 v9, 4, v8
	v_bitop3_b32 v9, v9, v8, 32 bitop3:0x6c
	v_ashrrev_i32_e32 v12, 31, v9
	v_lshrrev_b32_e32 v12, 26, v12
	v_add_u32_e32 v12, v9, v12
	v_lshlrev_b32_e32 v8, 3, v5
	v_ashrrev_i32_e32 v13, 6, v12
	v_and_b32_e32 v12, 0xc0, v12
	v_and_b32_e32 v8, -16, v8
	v_lshlrev_b32_e32 v5, 5, v5
	v_sub_u32_e32 v9, v9, v12
	v_add_u32_e32 v8, v13, v8
	v_and_b32_e32 v5, 32, v5
	v_ashrrev_i16_sdwa v9, v14, sext(v9) dst_sel:DWORD dst_unused:UNUSED_PAD src0_sel:DWORD src1_sel:BYTE_0
	v_add_u32_e32 v151, 0x10000, v150
	v_add_u32_sdwa v134, v5, sext(v9) dst_sel:DWORD dst_unused:UNUSED_PAD src0_sel:DWORD src1_sel:WORD_0
	v_ashrrev_i32_e32 v9, 31, v8
	v_readfirstlane_b32 s14, v151
	v_lshlrev_b64 v[136:137], 11, v[8:9]
	s_waitcnt vmcnt(8)
	v_add_u32_e32 v157, 0x12000, v150
	v_mov_b32_e32 v4, v2
	s_mov_b32 m0, s14
	v_lshl_add_u64 v[12:13], s[8:9], 0, v[136:137]
	v_readfirstlane_b32 s8, v157
	global_load_lds_dwordx4 v[10:11], off
	s_mov_b32 m0, s8
	s_lshl_b32 s8, s20, 11
	v_ashrrev_i32_e32 v135, 31, v134
	s_waitcnt lgkmcnt(0)
	s_add_u32 s8, s12, s8
	v_lshlrev_b64 v[8:9], 1, v[134:135]
	s_addc_u32 s9, s13, 0
	v_lshl_add_u64 v[12:13], v[12:13], 0, v[8:9]
	v_lshl_add_u64 v[14:15], s[8:9], 0, v[132:133]
	v_readfirstlane_b32 s14, v150
	global_load_lds_dwordx4 v[12:13], off
	v_lshl_add_u64 v[14:15], v[14:15], 0, v[6:7]
	s_mov_b32 m0, s14
	v_readfirstlane_b32 s14, v152
	global_load_lds_dwordx4 v[14:15], off
	s_mov_b32 m0, s14
	s_or_b32 s14, s0, 0x80
	s_ashr_i32 s15, s14, 31
	s_lshl_b64 s[14:15], s[14:15], 11
	s_add_u32 s14, s30, s14
	v_lshl_add_u64 v[16:17], s[8:9], 0, v[136:137]
	s_addc_u32 s15, s31, s15
	v_add_u32_e32 v159, 0x14000, v150
	v_lshl_add_u64 v[16:17], v[16:17], 0, v[8:9]
	v_lshl_add_u64 v[18:19], s[14:15], 0, v[132:133]
	v_readfirstlane_b32 s21, v159
	v_add_u32_e32 v160, 0x16000, v150
	global_load_lds_dwordx4 v[16:17], off
	v_lshl_add_u64 v[18:19], v[18:19], 0, v[6:7]
	s_mov_b32 m0, s21
	v_lshl_add_u64 v[20:21], s[14:15], 0, v[136:137]
	v_readfirstlane_b32 s14, v160
	global_load_lds_dwordx4 v[18:19], off
	s_mov_b32 m0, s14
	s_add_u32 s14, s8, 0x40000
	s_addc_u32 s15, s9, 0
	v_add_u32_e32 v162, 0x4000, v150
	v_lshl_add_u64 v[20:21], v[20:21], 0, v[8:9]
	v_lshl_add_u64 v[22:23], s[14:15], 0, v[132:133]
	v_readfirstlane_b32 s21, v162
	global_load_lds_dwordx4 v[20:21], off
	v_lshl_add_u64 v[22:23], v[22:23], 0, v[6:7]
	s_mov_b32 m0, s21
	v_add_u32_e32 v163, 0x6000, v150
	global_load_lds_dwordx4 v[22:23], off
	v_lshl_add_u64 v[22:23], s[14:15], 0, v[136:137]
	v_readfirstlane_b32 s14, v163
	v_lshl_add_u64 v[22:23], v[22:23], 0, v[8:9]
	s_mov_b32 m0, s14
	v_ashrrev_i32_e32 v5, 8, v3
	global_load_lds_dwordx4 v[22:23], off
	v_cmp_eq_u32_e32 vcc, 1, v5
	s_and_saveexec_b64 s[14:15], vcc
	s_cbranch_execz .LBB0_1014
	s_barrier

; template <int DK, int DV, int MODE>
; DI void att_gload(const AttArgs& a, int tile, u32x4 (&kr)[(64 * (DK / 8) + NT - 1) / NT], u32x4 (&vr)[(64 * (DV / 8) + NT - 1) / NT]) {
;   constexpr int CK = DK / 8, CV = DV / 8;
;   constexpr int NKL = (64 * CK + NT - 1) / NT, NVL = (64 * CV + NT - 1) / NT;
;   const int t = tid_opaque();
;   const int kbase = tile * 64;
; #pragma unroll
;   for (int i = 0; i < NKL; ++i) {
;     const int id = min(t + NT * i, 64 * CK - 1);
;     const int row = id / CK, c = id % CK;
;     if constexpr (MODE == 3) {
;       const bf16_t* src = (c < 8) ? (a.k + (size_t)(kbase + row) * a.ldk + c * 8) : (a.k2 + (size_t)(kbase + row) * a.ldk2 + (c - 8) * 8);
;       kr[i] = *(const u32x4*)src;
;     } else {
;       kr[i] = *(const u32x4*)(a.k + (size_t)(kbase + row) * a.ldk + c * 8);
;     }
;   }
; #pragma unroll
;   for (int i = 0; i < NVL; ++i) {
;     const int id = t + NT * i;
;     const int row = id / CV, c = id % CV;
;     vr[i] = *(const u32x4*)(a.v + (size_t)(kbase + row) * a.ldv + c * 8);
;   }
; }
; template <int DK, int DV>
; DI void att_swrite(int buf, const u32x4 (&kr)[(64 * (DK / 8) + NT - 1) / NT], const u32x4 (&vr)[(64 * (DV / 8) + NT - 1) / NT]) {
;   constexpr int CK = DK / 8, CV = DV / 8;
;   constexpr int KST = DK * 2 + 16, VST = DV * 2 + 16;
;   constexpr int KBYTES = 64 * KST, VBYTES = 64 * VST, BUFB = KBYTES + VBYTES;
;   constexpr int NKL = (64 * CK + NT - 1) / NT, NVL = (64 * CV + NT - 1) / NT;
;   const int t = tid_opaque();
; #pragma unroll
;   for (int i = 0; i < NKL; ++i) {
;     const int id = t + NT * i;
;     const int row = id / CK, c = id % CK;
;     if (id < 64 * CK) *(u32x4*)(smem + buf * BUFB + row * KST + c * 16) = kr[i];
;   }
; #pragma unroll
;   for (int i = 0; i < NVL; ++i) {
;     const int id = t + NT * i;
;     const int row = id / CV, c = id % CV;
;     *(u32x4*)(smem + buf * BUFB + KBYTES + row * VST + c * 16) = vr[i];
;   }
; }
; __global__ void __launch_bounds__(512, 2) mega(Params p) {
;     ...
;     for (int item = bid; item < 256; item += nb) {
;       const int pl = item & 7, rest = item >> 3;
;       const int qt = rest & 7, pg = rest >> 3;
;       const int pair = pg * 8 + pl;
;       const int b = pair >> 2, hd = pair & 3;
;       AttArgs a{};
;       a.q = G_XQ + (size_t)b * SEQ * 512 + hd * 128; a.ldq = 512;
;       a.k = G_MEMKV + (size_t)b * 256 * 1024 + hd * 128; a.ldk = 1024;
.LBB0_1077:
	s_ashr_i32 s1, s14, 3
	s_and_b32 s0, s14, 4
	s_and_b32 s1, s1, -8
	s_or_b32 s0, s1, s0
	s_ashr_i32 s4, s0, 2
	s_mov_b32 s0, 25
	s_ashr_i32 s1, s0, 31
	s_lshl_b64 s[0:1], s[0:1], 3
	s_add_u32 s0, s70, s0
	s_addc_u32 s1, s71, s1
	v_readlane_b32 s0, v255, 60
	v_readlane_b32 s1, v255, 61
	s_nop 4
	s_ashr_i32 s5, s4, 31
	s_lshl_b64 s[2:3], s[4:5], 21
	v_mov_b32_e32 v3, v224
	v_mov_b32_e32 v163, v2
	s_waitcnt lgkmcnt(0)
	s_add_u32 s0, s0, s2
	s_addc_u32 s1, s1, s3
	s_lshl_b32 s2, s14, 7
	s_and_b32 s2, s2, 0x180
	s_lshl_b32 s15, s2, 1
	s_add_u32 s8, s0, s15
	s_mov_b32 s0, 25
	s_addc_u32 s9, s1, 0
	s_ashr_i32 s1, s0, 31
	s_lshl_b64 s[0:1], s[0:1], 3
	s_add_u32 s0, s70, s0
	s_addc_u32 s1, s71, s1
	v_readlane_b32 s0, v255, 60
	v_readlane_b32 s1, v255, 61
	s_nop 4
	s_lshl_b64 s[6:7], s[4:5], 19
	v_mov_b32_e32 v10, v224
	v_mov_b32_e32 v22, v224
	s_waitcnt lgkmcnt(0)
	s_add_u32 s0, s0, s6
	s_addc_u32 s1, s1, s7
	s_add_u32 s0, s0, s15
	s_addc_u32 s1, s1, 0
	s_add_u32 s2, s0, 0xbc00000
	s_mov_b32 s0, 25
	s_addc_u32 s3, s1, 0
	s_ashr_i32 s1, s0, 31
	s_lshl_b64 s[0:1], s[0:1], 3
	s_add_u32 s0, s70, s0
	s_addc_u32 s1, s71, s1
	v_readlane_b32 s0, v255, 60
	v_readlane_b32 s1, v255, 61
	s_nop 4
	s_waitcnt lgkmcnt(0)
	s_add_u32 s0, s0, s6
	s_addc_u32 s1, s1, s7
	s_add_u32 s0, s0, s15
	s_addc_u32 s1, s1, 0
	s_add_u32 s6, s0, 0xbc00400
	s_mov_b32 s0, 25
	s_addc_u32 s7, s1, 0
	s_ashr_i32 s1, s0, 31
	s_lshl_b64 s[0:1], s[0:1], 3
	s_add_u32 s0, s70, s0
	s_addc_u32 s1, s71, s1
	s_lshl_b32 s12, s14, 5
	s_and_b32 s12, s12, 0x700
	v_ashrrev_i32_e32 v0, 1, v3
	v_and_b32_e32 v0, 0xffffffe0, v0
	v_and_b32_e32 v20, 31, v3
	v_add_u32_e32 v0, s12, v0
	v_or_b32_e32 v0, v0, v20
	v_ashrrev_i32_e32 v1, 31, v0
	v_bfe_u32 v21, v3, 5, 1
	v_lshlrev_b64 v[4:5], 10, v[0:1]
	v_lshl_add_u64 v[4:5], s[8:9], 0, v[4:5]
	v_lshlrev_b32_e32 v162, 4, v21
	v_lshl_add_u64 v[4:5], v[4:5], 0, v[162:163]
	s_mov_b64 s[8:9], 0x2000000
	v_lshl_add_u64 v[6:7], v[4:5], 0, s[8:9]
	s_brev_b32 s8, 64
	v_add_co_u32_e32 v4, vcc, s8, v4
	s_movk_i32 s8, 0x400
	s_nop 0
	v_addc_co_u32_e32 v5, vcc, 0, v5, vcc
	global_load_dwordx4 v[136:139], v[6:7], off offset:32
	global_load_dwordx4 v[132:135], v[6:7], off offset:64
	global_load_dwordx4 v[128:131], v[6:7], off offset:96
	global_load_dwordx4 v[124:127], v[6:7], off offset:128
	global_load_dwordx4 v[120:123], v[6:7], off offset:160
	global_load_dwordx4 v[116:119], v[6:7], off offset:192
	global_load_dwordx4 v[140:143], v[4:5], off
	global_load_dwordx4 v[112:115], v[6:7], off offset:224
	s_nop 0
	v_min_i32_e32 v5, 0x3ff, v10
	v_ashrrev_i32_e32 v4, 31, v5
	v_lshrrev_b32_e32 v4, 28, v4
	v_add_u32_e32 v6, v5, v4
	v_ashrrev_i32_e32 v4, 4, v6
	v_and_b32_e32 v6, 0x1ffffff0, v6
	v_sub_u32_e32 v6, v5, v6
	v_ashrrev_i32_e32 v5, 31, v4
	v_lshlrev_b64 v[4:5], 11, v[4:5]
	v_lshlrev_b32_e32 v6, 3, v6
	v_lshl_add_u64 v[4:5], s[2:3], 0, v[4:5]
	v_ashrrev_i32_e32 v7, 31, v6
	v_add_u32_e32 v12, 0x200, v10
	v_lshl_add_u64 v[4:5], v[6:7], 1, v[4:5]
	v_min_i32_e32 v7, 0x3ff, v12
	v_ashrrev_i32_e32 v6, 31, v7
	v_lshrrev_b32_e32 v6, 28, v6
	v_add_u32_e32 v8, v7, v6
	v_ashrrev_i32_e32 v6, 4, v8
	v_and_b32_e32 v8, 0x1ffffff0, v8
	v_sub_u32_e32 v8, v7, v8
	v_ashrrev_i32_e32 v7, 31, v6
	v_lshlrev_b64 v[6:7], 11, v[6:7]
	v_lshlrev_b32_e32 v8, 3, v8
	v_lshl_add_u64 v[6:7], s[2:3], 0, v[6:7]
	v_ashrrev_i32_e32 v9, 31, v8
	v_lshl_add_u64 v[6:7], v[8:9], 1, v[6:7]
	v_ashrrev_i32_e32 v8, 31, v10
	v_lshrrev_b32_e32 v8, 28, v8
	v_add_u32_e32 v9, v10, v8
	v_ashrrev_i32_e32 v8, 4, v9
	v_and_b32_e32 v9, 0x1ffffff0, v9
	v_sub_u32_e32 v10, v10, v9
	v_ashrrev_i32_e32 v9, 31, v8
	v_lshlrev_b64 v[8:9], 11, v[8:9]
	v_lshlrev_b32_e32 v10, 3, v10
	v_lshl_add_u64 v[8:9], s[6:7], 0, v[8:9]
	v_ashrrev_i32_e32 v11, 31, v10
	v_lshl_add_u64 v[8:9], v[10:11], 1, v[8:9]
	v_ashrrev_i32_e32 v10, 31, v12
	v_lshrrev_b32_e32 v10, 28, v10
	v_add_u32_e32 v11, v12, v10
	v_ashrrev_i32_e32 v10, 4, v11
	v_and_b32_e32 v11, 0x1ffffff0, v11
	v_sub_u32_e32 v12, v12, v11
	v_ashrrev_i32_e32 v11, 31, v10
	v_lshlrev_b64 v[10:11], 11, v[10:11]
	v_lshlrev_b32_e32 v12, 3, v12
	v_lshl_add_u64 v[10:11], s[6:7], 0, v[10:11]
	v_ashrrev_i32_e32 v13, 31, v12
	v_lshl_add_u64 v[10:11], v[12:13], 1, v[10:11]
	global_load_dwordx4 v[16:19], v[4:5], off
	s_nop 0
	global_load_dwordx4 v[4:7], v[6:7], off
	s_nop 0
	global_load_dwordx4 v[12:15], v[8:9], off
	s_nop 0
	global_load_dwordx4 v[8:11], v[10:11], off
	s_nop 0
	v_ashrrev_i32_e32 v23, 31, v22
	v_cmp_gt_i32_e32 vcc, s8, v22
	v_lshrrev_b32_e32 v23, 28, v23
	s_and_saveexec_b64 s[8:9], vcc
	s_cbranch_execz .LBB0_1079
	v_add_u32_e32 v24, v22, v23
	v_and_b32_e32 v25, 0xffffff0, v24
	v_lshrrev_b32_e32 v24, 4, v24
	s_movk_i32 s12, 0x110
	v_sub_u32_e32 v25, v22, v25
	v_mul_lo_u32 v24, v24, s12
	v_lshl_add_u32 v24, v25, 4, v24
	s_waitcnt vmcnt(3)
	ds_write_b128 v24, v[16:19]

; #define BAR8 __builtin_amdgcn_s_barrier()
; #define G_XF (outp())
; #define G_SS ((float*)(wsp() + OFF_SS))
;     ...
;     STAGE8(SB8(0, 0), Bt, K, bcol, 0); STAGE8(SA8(0, 0), A, lda, brow, 0);
;     STAGE8(SB8(0, 1), Bt, K, bcol + 128, 0); STAGE8(SA8(0, 1), A, lda, brow + 128, 0);
;   }
;   if (wr == 1) BAR8;
; __global__ void __launch_bounds__(512, 2) mega(Params p) {
;     ...
;     for (int item = bid; item < 4 * 64; item += nb) {
;       const int nt = item >> 6, mt = item & 63;
;       e.ss = nullptr; e.xf = G_XF; e.xb = G_XB; e.ss_out = G_SS;
;       gemm_tile<EPI_RESID, 256, false>(G_XO, 512, wb + W_XO, 512, mt * 256, nt * 256, e);
.LBB0_1149:
	s_mov_b32 s0, 24
	s_mov_b32 s0, 25
	s_ashr_i32 s1, s0, 31
	s_lshl_b64 s[0:1], s[0:1], 3
	s_add_u32 s0, s70, s0
	s_addc_u32 s1, s71, s1
	v_readlane_b32 s6, v255, 60
	v_readlane_b32 s7, v255, 61
	s_nop 4
	s_mov_b32 s0, 25
	s_ashr_i32 s1, s0, 31
	s_lshl_b64 s[0:1], s[0:1], 3
	s_add_u32 s0, s70, s0
	s_addc_u32 s1, s71, s1
	s_mov_b32 s2, 25
	v_readlane_b32 s0, v255, 60
	v_readlane_b32 s1, v255, 61
	s_nop 4
	s_ashr_i32 s3, s2, 31
	s_lshl_b64 s[2:3], s[2:3], 3
	s_add_u32 s2, s70, s2
	s_addc_u32 s3, s71, s3
	v_mov_b32_e32 v3, v224
	v_readlane_b32 s2, v255, 60
	v_readlane_b32 s3, v255, 61
	s_nop 4
	v_mov_b32_e32 v18, 1
	v_bfe_i32 v1, v3, 27, 1
	s_waitcnt vmcnt(10)
	v_lshlrev_b32_e32 v150, 4, v3
	v_lshrrev_b32_e32 v1, 22, v1
	v_add_u32_e32 v1, v150, v1
	v_and_b32_e32 v1, 0xfffffc00, v1
	v_ashrrev_i32_e32 v0, 31, v3
	v_sub_u32_e32 v1, v150, v1
	v_lshrrev_b32_e32 v0, 26, v0
	v_lshrrev_b32_e32 v5, 4, v1
	v_add_u32_e32 v0, v3, v0
	v_bitop3_b32 v5, v5, v1, 32 bitop3:0x6c
	v_ashrrev_i32_e32 v1, 31, v1
	s_waitcnt lgkmcnt(0)
	s_add_u32 s29, s2, 0x3000000
	v_ashrrev_i32_e32 v0, 6, v0
	v_lshrrev_b32_e32 v1, 26, v1
	s_addc_u32 s33, s3, 0
	s_lshl_b32 s8, s24, 8
	v_lshlrev_b32_e32 v6, 3, v0
	v_add_u32_e32 v1, v5, v1
	s_and_b32 s25, s8, 0x3f00
	s_lshl_b32 s8, s24, 2
	v_and_b32_e32 v6, -16, v6
	v_ashrrev_i32_e32 v1, 6, v1
	s_and_b32 s8, s8, 0xffffff00
	v_add_u32_e32 v16, v1, v6
	v_mul_i32_i24_e32 v1, 64, v1
	s_ashr_i32 s9, s8, 31
	v_lshlrev_b32_e32 v0, 5, v0
	v_sub_u32_e32 v1, v5, v1
	s_waitcnt vmcnt(9)
	v_add_u32_e32 v152, 0x2000, v150
	s_lshl_b64 s[12:13], s[8:9], 10
	v_and_b32_e32 v0, 32, v0
	v_ashrrev_i16_sdwa v1, v18, sext(v1) dst_sel:DWORD dst_unused:UNUSED_PAD src0_sel:DWORD src1_sel:BYTE_0
	v_ashrrev_i32_e32 v5, 31, v152
	s_add_u32 s12, s14, s12
	v_add_u32_sdwa v0, v0, sext(v1) dst_sel:DWORD dst_unused:UNUSED_PAD src0_sel:DWORD src1_sel:WORD_0
	v_ashrrev_i32_e32 v17, 31, v16
	v_lshrrev_b32_e32 v5, 22, v5
	s_addc_u32 s13, s15, s13
	v_lshlrev_b64 v[6:7], 10, v[16:17]
	v_ashrrev_i32_e32 v1, 31, v0
	v_add_u32_e32 v5, v152, v5
	v_lshl_add_u64 v[10:11], s[12:13], 0, v[6:7]
	v_lshlrev_b64 v[8:9], 1, v[0:1]
	v_ashrrev_i32_e32 v5, 10, v5
	v_lshl_add_u64 v[14:15], v[10:11], 0, v[8:9]
	v_mul_i32_i24_e32 v10, 0x400, v5
	v_sub_u32_e32 v10, v152, v10
	v_lshrrev_b32_e32 v11, 4, v10
	v_bitop3_b32 v10, v11, v10, 32 bitop3:0x6c
	v_ashrrev_i32_e32 v12, 31, v10
	v_lshrrev_b32_e32 v12, 26, v12
	v_lshlrev_b32_e32 v11, 3, v5
	v_add_u32_e32 v12, v10, v12
	v_and_b32_e32 v11, -16, v11
	v_ashrrev_i32_e32 v13, 6, v12
	v_add_u32_e32 v24, v13, v11
	v_and_b32_e32 v11, 0xc0, v12
	v_lshlrev_b32_e32 v5, 5, v5
	v_sub_u32_e32 v10, v10, v11
	v_add_u32_e32 v151, 0x10000, v150
	v_and_b32_e32 v5, 32, v5
	v_ashrrev_i16_sdwa v10, v18, sext(v10) dst_sel:DWORD dst_unused:UNUSED_PAD src0_sel:DWORD src1_sel:BYTE_0
	v_ashrrev_i32_e32 v25, 31, v24
	v_readfirstlane_b32 s27, v151
	v_add_u32_sdwa v132, v5, sext(v10) dst_sel:DWORD dst_unused:UNUSED_PAD src0_sel:DWORD src1_sel:WORD_0
	v_lshlrev_b64 v[10:11], 10, v[24:25]
	s_waitcnt vmcnt(8)
	v_add_u32_e32 v157, 0x12000, v150
	v_mov_b32_e32 v4, v2
	s_mov_b32 m0, s27
	v_lshl_add_u64 v[18:19], s[12:13], 0, v[10:11]
	v_readfirstlane_b32 s12, v157
	global_load_lds_dwordx4 v[14:15], off
	v_ashrrev_i32_e32 v133, 31, v132
	s_mov_b32 m0, s12
	s_lshl_b32 s27, s25, 9
	s_lshl_b32 s12, s25, 10
	v_lshlrev_b64 v[12:13], 1, v[132:133]
	s_add_u32 s12, s29, s12
	v_lshl_add_u64 v[18:19], v[18:19], 0, v[12:13]
	s_addc_u32 s13, s33, 0
	v_readfirstlane_b32 s30, v150
	global_load_lds_dwordx4 v[18:19], off
	v_lshl_add_u64 v[20:21], s[12:13], 0, v[6:7]
	s_mov_b32 m0, s30
	s_or_b32 s30, s8, 0x80
	v_lshl_add_u64 v[20:21], v[20:21], 0, v[8:9]
	v_lshl_add_u64 v[22:23], s[12:13], 0, v[10:11]
	v_readfirstlane_b32 s12, v152
	s_ashr_i32 s31, s30, 31
	global_load_lds_dwordx4 v[20:21], off
	s_mov_b32 m0, s12
	s_lshl_b64 s[12:13], s[30:31], 10
	s_add_u32 s12, s14, s12
	s_addc_u32 s13, s15, s13
	v_add_u32_e32 v159, 0x14000, v150
	v_lshl_add_u64 v[22:23], v[22:23], 0, v[12:13]
	v_lshl_add_u64 v[26:27], s[12:13], 0, v[6:7]
	v_readfirstlane_b32 s31, v159
	v_add_u32_e32 v161, 0x16000, v150
	s_bitset1_b32 s27, 16
	global_load_lds_dwordx4 v[22:23], off
	v_lshl_add_u64 v[26:27], v[26:27], 0, v[8:9]
	s_mov_b32 m0, s31
	v_lshl_add_u64 v[28:29], s[12:13], 0, v[10:11]
	v_readfirstlane_b32 s12, v161
	s_lshl_b32 s27, s27, 1
	global_load_lds_dwordx4 v[26:27], off
	s_mov_b32 m0, s12
	s_add_u32 s12, s29, s27
	s_addc_u32 s13, s33, 0
	v_add_u32_e32 v162, 0x4000, v150
	v_lshl_add_u64 v[28:29], v[28:29], 0, v[12:13]
	v_lshl_add_u64 v[30:31], s[12:13], 0, v[6:7]
	v_readfirstlane_b32 s29, v162
	global_load_lds_dwordx4 v[28:29], off
	v_lshl_add_u64 v[30:31], v[30:31], 0, v[8:9]
	s_mov_b32 m0, s29
	v_add_u32_e32 v163, 0x6000, v150
	global_load_lds_dwordx4 v[30:31], off
	v_lshl_add_u64 v[30:31], s[12:13], 0, v[10:11]
	v_readfirstlane_b32 s12, v163
	v_lshl_add_u64 v[30:31], v[30:31], 0, v[12:13]
	s_mov_b32 m0, s12
	v_ashrrev_i32_e32 v5, 8, v3
	global_load_lds_dwordx4 v[30:31], off
	v_cmp_eq_u32_e32 vcc, 1, v5
	s_and_saveexec_b64 s[12:13], vcc
	s_cbranch_execz .LBB0_1151
	s_barrier

; #define WAIT_V0() asm volatile("s_waitcnt vmcnt(0)" ::: "memory")
; #define G_SS ((float*)(wsp() + OFF_SS))
; template <int EPI, int BN, bool F16>
; DI void gemm_tile(const bf16_t* __restrict__ A, int lda, const bf16_t* __restrict__ W, int K, int m0, int n0, const Ep& e) {
;     ...
;   const int grow = w * 8 + (l >> 3);
;   const int gch = (l & 7) ^ ((grow >> 1) & 7);
;   const bf16_t* ap = A + (size_t)(m0 + grow) * lda + gch * 8;
;   const bf16_t* wp = W + (size_t)(n0 + grow) * K + gch * 8;
;   unsigned char* lbase = smem + w * 1024;
;   const int sw = (r >> 1) & 7;
;   const unsigned char* ab = smem + (wm * (MI * 32) + r) * 128;
;   const unsigned char* bb = smem + 32768 + (wn * 64 + r) * 128;
;   const int nk = K >> 6;
;     ...
;   G_STAGE(0, 0)
;   WAIT_V0();
;   __syncthreads();
; __global__ void __launch_bounds__(512, 2) mega(Params p) {
;     ...
;     for (int item = bid; item < 20 * 64 + 4 * 64; item += nb) {
;       e.ss = G_SS; e.nss = 16; e.inv_n = 1.f / 1024.f; e.out = G_ACT; e.ldo = 2816;
;       if (item < 1280) {
;         const int nt = item >> 6, mt = item & 63;
;         const int nxt = item + nb;
;         const bool chain = nxt < 1280;
;         gemm_tile256<EPI_GU, true>(G_XB, DM, wb + W_GU, DM, mt * 256, nt * 256, e, pre7, chain ? (nxt & 63) * 256 : -1, (nxt >> 6) * 256);
;         pre7 = chain;
;       } else {
;         const int it = item - 1280;
;         const int nt = it >> 6, mt = it & 63;
;         gemm_tile<EPI_GU, 128, true>(G_XB, DM, wb + W_GU, DM, mt * 256, 5120 + nt * 128, e);
.LBB0_1245:
	s_mov_b32 s0, 25
	s_ashr_i32 s1, s0, 31
	s_lshr_b32 s12, s24, 8
	s_lshl_b64 s[0:1], s[0:1], 3
	s_add_u32 s0, s70, s0
	s_addc_u32 s1, s71, s1
	v_readlane_b32 s0, v255, 60
	v_readlane_b32 s1, v255, 61
	s_nop 4
	s_mov_b32 s2, 25
	s_waitcnt lgkmcnt(0)
	s_add_u32 s38, s0, 0xf640000
	s_addc_u32 s39, s1, 0
	s_ashr_i32 s3, s2, 31
	s_lshl_b64 s[0:1], s[2:3], 3
	s_add_u32 s0, s70, s0
	s_addc_u32 s1, s71, s1
	v_readlane_b32 s0, v255, 60
	v_readlane_b32 s1, v255, 61
	s_nop 4
	s_waitcnt lgkmcnt(0)
	s_add_u32 s30, s0, 0x2000000
	s_addc_u32 s31, s1, 0
	s_cmpk_gt_i32 s25, 0x4ff
	s_mov_b64 s[0:1], -1
	s_cbranch_scc0 .LBB0_1253
	s_mov_b32 s0, 25
	s_ashr_i32 s1, s0, 31
	s_and_b32 s27, s12, 63
	s_and_b32 s29, s21, 0x7fffff80
	s_lshl_b64 s[0:1], s[0:1], 3
	s_add_u32 s0, s70, s0
	s_addc_u32 s1, s71, s1
	v_readlane_b32 s2, v255, 60
	v_readlane_b32 s3, v255, 61
	s_nop 4
	s_lshl_b32 s0, s25, 8
	v_mov_b32_e32 v3, v224
	s_and_b32 s13, s0, 0x3f00
	s_lshl_b32 s0, s25, 1
	s_and_b32 s0, s0, 0x7fffff80
	v_ashrrev_i32_e32 v8, 6, v3
	v_lshlrev_b32_e32 v9, 3, v8
	v_bfe_u32 v10, v3, 3, 3
	s_addk_i32 s0, 0xa00
	v_or_b32_e32 v6, v9, v10
	v_lshrrev_b32_e32 v11, 1, v6
	v_add_u32_e32 v0, s13, v6
	v_add_u32_e32 v6, s0, v6
	v_xor_b32_e32 v4, v11, v3
	v_ashrrev_i32_e32 v1, 31, v0
	v_ashrrev_i32_e32 v7, 31, v6
	v_lshlrev_b64 v[0:1], 11, v[0:1]
	v_lshlrev_b32_e32 v4, 4, v4
	v_lshlrev_b64 v[6:7], 11, v[6:7]
	s_waitcnt lgkmcnt(0)
	v_lshl_add_u64 v[0:1], s[2:3], 0, v[0:1]
	v_and_b32_e32 v4, 0x70, v4
	v_mov_b32_e32 v5, v2
	v_lshl_add_u64 v[6:7], s[4:5], 0, v[6:7]
	v_lshl_add_u64 v[0:1], v[0:1], 0, v[4:5]
	v_lshl_add_u64 v[4:5], v[6:7], 0, v[4:5]
	v_lshlrev_b32_e32 v79, 10, v8
	v_ashrrev_i32_e32 v6, 1, v3
	v_and_b32_e32 v76, 31, v3
	v_and_b32_e32 v77, 0xffffffc0, v6
	v_add_u32_e32 v82, 0x8000, v79
	v_readfirstlane_b32 s1, v79
	v_or_b32_e32 v6, v77, v76
	s_mov_b32 m0, s1
	v_readfirstlane_b32 s1, v82
	v_add_u32_e32 v83, 0x2000, v79
	v_lshlrev_b32_e32 v80, 7, v6
	v_lshlrev_b32_e32 v6, 7, v3
	global_load_lds_dwordx4 v[0:1], off
	s_mov_b32 m0, s1
	s_mov_b64 s[14:15], 0x20000
	v_readfirstlane_b32 s1, v83
	v_add_u32_e32 v84, 0xa000, v79
	v_and_b32_e32 v81, 0x2f80, v6
	global_load_lds_dwordx4 v[4:5], off
	v_lshl_add_u64 v[6:7], v[0:1], 0, s[14:15]
	s_mov_b32 m0, s1
	v_readfirstlane_b32 s1, v84
	v_add_u32_e32 v85, 0x4000, v79
	global_load_lds_dwordx4 v[6:7], off
	v_lshl_add_u64 v[4:5], v[4:5], 0, s[14:15]
	s_mov_b32 m0, s1
	s_mov_b64 s[14:15], 0x40000
	v_readfirstlane_b32 s1, v85
	v_add_u32_e32 v86, 0x6000, v79
	global_load_lds_dwordx4 v[4:5], off
	v_lshl_add_u64 v[4:5], v[0:1], 0, s[14:15]
	s_mov_b32 m0, s1
	s_mov_b64 s[14:15], 0x60000
	v_readfirstlane_b32 s1, v86
	global_load_lds_dwordx4 v[4:5], off
	v_lshl_add_u64 v[0:1], v[0:1], 0, s[14:15]
	s_mov_b32 m0, s1
	v_lshl_or_b32 v4, s27, 8, v10
	global_load_lds_dwordx4 v[0:1], off
	v_add_u32_e32 v4, v4, v9
	v_ashrrev_i32_e32 v5, 31, v4
	v_lshlrev_b64 v[4:5], 11, v[4:5]
	v_lshrrev_b32_e32 v8, 1, v3
	v_bfe_u32 v78, v3, 5, 1
	v_lshl_add_u64 v[68:69], s[2:3], 0, v[4:5]
	v_or_b32_e32 v4, s29, v10
	s_movk_i32 s1, 0xa00
	v_bfe_u32 v0, v3, 1, 3
	v_bitop3_b32 v1, v78, v8, 7 bitop3:0x78
	v_add3_u32 v4, v4, v9, s1
	v_lshlrev_b32_e32 v89, 4, v1
	v_bitop3_b32 v1, v78, v0, 2 bitop3:0x36
	v_ashrrev_i32_e32 v5, 31, v4
	s_waitcnt vmcnt(0)
	v_lshlrev_b32_e32 v90, 4, v1
	v_bitop3_b32 v1, v78, v0, 4 bitop3:0x36
	v_bitop3_b32 v0, v78, v0, 6 bitop3:0x36
	v_lshlrev_b64 v[4:5], 11, v[4:5]
	v_lshlrev_b32_e32 v92, 4, v0
	v_bitop3_b32 v0, v11, 7, v3 bitop3:0x48
	v_lshl_add_u64 v[70:71], s[6:7], 0, v[4:5]
	v_mov_b32_e32 v4, 0
	v_add_u32_e32 v87, 0x10000, v79
	v_add_u32_e32 v88, 0x18000, v79
	v_lshlrev_b32_e32 v91, 4, v1
	v_add_u32_e32 v93, 0x10000, v80
	v_or_b32_e32 v94, 0x18000, v81
	v_add_u32_e32 v95, 0x12000, v79
	v_add_u32_e32 v96, 0x1a000, v79
	v_add_u32_e32 v97, 0x14000, v79
	v_add_u32_e32 v98, 0x16000, v79
	v_lshlrev_b32_e32 v0, 4, v0
	v_mov_b32_e32 v1, v2
	s_mov_b32 s1, 0
	v_mov_b32_e32 v5, v4
	v_mov_b64_e32 v[6:7], v[4:5]
	v_mov_b64_e32 v[8:9], v[4:5]
	v_mov_b64_e32 v[10:11], v[4:5]
	v_mov_b64_e32 v[12:13], v[4:5]
	v_mov_b64_e32 v[14:15], v[4:5]
	v_mov_b64_e32 v[16:17], v[4:5]
	v_mov_b64_e32 v[18:19], v[4:5]
	v_mov_b64_e32 v[20:21], v[4:5]
	v_mov_b64_e32 v[22:23], v[4:5]
	v_mov_b64_e32 v[24:25], v[4:5]
	v_mov_b64_e32 v[26:27], v[4:5]
	v_mov_b64_e32 v[28:29], v[4:5]
	v_mov_b64_e32 v[30:31], v[4:5]
	v_mov_b64_e32 v[32:33], v[4:5]
	v_mov_b64_e32 v[34:35], v[4:5]
	v_mov_b64_e32 v[36:37], v[4:5]
	v_mov_b64_e32 v[38:39], v[4:5]
	v_mov_b64_e32 v[40:41], v[4:5]
	v_mov_b64_e32 v[42:43], v[4:5]
	v_mov_b64_e32 v[44:45], v[4:5]
	v_mov_b64_e32 v[46:47], v[4:5]
	v_mov_b64_e32 v[48:49], v[4:5]
	v_mov_b64_e32 v[50:51], v[4:5]
	v_mov_b64_e32 v[52:53], v[4:5]
	v_mov_b64_e32 v[54:55], v[4:5]
	v_mov_b64_e32 v[56:57], v[4:5]
	v_mov_b64_e32 v[58:59], v[4:5]
	v_mov_b64_e32 v[60:61], v[4:5]
	v_mov_b64_e32 v[62:63], v[4:5]
	v_mov_b64_e32 v[64:65], v[4:5]
	v_mov_b64_e32 v[66:67], v[4:5]
	s_waitcnt vmcnt(0) lgkmcnt(0)
	s_barrier
	s_branch .LBB0_1248

; #define WAIT_V8(n) asm volatile("s_waitcnt vmcnt(" #n ")" ::: "memory")
; #define BAR8 __builtin_amdgcn_s_barrier()
; #define G_SS ((float*)(wsp() + OFF_SS))
;     ...
;   if (!pre) {
;     STAGE8(SB8(0, 0), Bt, K, bcol, 0); STAGE8(SA8(0, 0), A, lda, brow, 0);
;     STAGE8(SB8(0, 1), Bt, K, bcol + 128, 0); STAGE8(SA8(0, 1), A, lda, brow + 128, 0);
;   }
;   if (wr == 1) BAR8;
;   WAIT_V8(4); BAR8;
;   STAGE8(SB8(1, 0), Bt, K, bcol, 1); STAGE8(SA8(1, 0), A, lda, brow, 1); STAGE8(SB8(1, 1), Bt, K, bcol + 128, 1);
;   WAIT_V8(6); BAR8;
; __global__ void __launch_bounds__(512, 2) mega(Params p) {
;     ...
;     for (int item = bid; item < 20 * 64 + 4 * 64; item += nb) {
;       e.ss = G_SS; e.nss = 16; e.inv_n = 1.f / 1024.f; e.out = G_ACT; e.ldo = 2816;
;       if (item < 1280) {
;         const int nt = item >> 6, mt = item & 63;
;         const int nxt = item + nb;
;         const bool chain = nxt < 1280;
;         gemm_tile256<EPI_GU, true>(G_XB, DM, wb + W_GU, DM, mt * 256, nt * 256, e, pre7, chain ? (nxt & 63) * 256 : -1, (nxt >> 6) * 256);
.LBB0_1253:
	s_and_b64 vcc, exec, s[0:1]
	s_cbranch_vccz .LBB0_1266
	s_mov_b32 s0, 25
	s_ashr_i32 s1, s0, 31
	s_xor_b64 s[8:9], s[8:9], -1
	s_lshl_b64 s[0:1], s[0:1], 3
	s_add_u32 s0, s70, s0
	s_addc_u32 s1, s71, s1
	v_readlane_b32 s2, v255, 60
	v_readlane_b32 s3, v255, 61
	s_nop 4
	s_lshl_b32 s0, s25, 8
	v_mov_b32_e32 v3, v224
	s_and_b32 s27, s0, 0x3f00
	s_lshl_b32 s0, s25, 2
	s_and_b32 s0, s0, 0xffffff00
	s_waitcnt vmcnt(10)
	v_lshlrev_b32_e32 v150, 4, v3
	v_ashrrev_i32_e32 v0, 31, v3
	v_bfe_i32 v5, v3, 27, 1
	v_mov_b32_e32 v4, v2
	s_andn2_b64 vcc, exec, s[8:9]
	v_lshrrev_b32_e32 v1, 26, v0
	v_lshrrev_b32_e32 v0, 22, v5
	v_add_u32_e32 v151, 0x10000, v150
	s_waitcnt vmcnt(9)
	v_add_u32_e32 v152, 0x2000, v150
	v_add_u32_e32 v153, 0x12000, v150
	v_add_u32_e32 v154, 0x14000, v150
	v_add_u32_e32 v155, 0x16000, v150
	s_waitcnt vmcnt(8)
	v_add_u32_e32 v156, 0x4000, v150
	v_add_u32_e32 v157, 0x6000, v150
	s_cbranch_vccnz .LBB0_1256
	v_add_u32_e32 v6, v150, v0
	v_and_b32_e32 v6, 0xfffffc00, v6
	v_sub_u32_e32 v6, v150, v6
	v_lshrrev_b32_e32 v7, 4, v6
	v_add_u32_e32 v5, v3, v1
	v_bitop3_b32 v7, v7, v6, 32 bitop3:0x6c
	v_ashrrev_i32_e32 v6, 31, v6
	v_ashrrev_i32_e32 v5, 6, v5
	v_lshrrev_b32_e32 v6, 26, v6
	v_lshlrev_b32_e32 v8, 3, v5
	v_add_u32_e32 v6, v7, v6
	v_and_b32_e32 v8, -16, v8
	v_ashrrev_i32_e32 v9, 6, v6
	v_add_u32_e32 v6, v9, v8
	v_mul_i32_i24_e32 v8, 64, v9
	s_ashr_i32 s1, s0, 31
	v_lshlrev_b32_e32 v5, 5, v5
	v_sub_u32_e32 v7, v7, v8
	v_mov_b32_e32 v14, 1
	s_lshl_b64 s[8:9], s[0:1], 11
	v_and_b32_e32 v5, 32, v5
	v_ashrrev_i16_sdwa v7, v14, sext(v7) dst_sel:DWORD dst_unused:UNUSED_PAD src0_sel:DWORD src1_sel:BYTE_0
	s_add_u32 s8, s4, s8
	v_add_u32_sdwa v8, v5, sext(v7) dst_sel:DWORD dst_unused:UNUSED_PAD src0_sel:DWORD src1_sel:WORD_0
	v_ashrrev_i32_e32 v7, 31, v6
	v_ashrrev_i32_e32 v5, 31, v152
	s_addc_u32 s9, s5, s9
	v_lshlrev_b64 v[6:7], 11, v[6:7]
	v_ashrrev_i32_e32 v9, 31, v8
	v_lshrrev_b32_e32 v5, 22, v5
	v_lshl_add_u64 v[10:11], s[8:9], 0, v[6:7]
	v_lshlrev_b64 v[8:9], 1, v[8:9]
	v_readfirstlane_b32 s1, v151
	v_add_u32_e32 v5, v152, v5
	v_lshl_add_u64 v[10:11], v[10:11], 0, v[8:9]
	s_mov_b32 m0, s1
	v_ashrrev_i32_e32 v5, 10, v5
	global_load_lds_dwordx4 v[10:11], off
	v_mul_i32_i24_e32 v10, 0x400, v5
	v_sub_u32_e32 v10, v152, v10
	v_lshrrev_b32_e32 v11, 4, v10
	v_bitop3_b32 v11, v11, v10, 32 bitop3:0x6c
	v_ashrrev_i32_e32 v12, 31, v11
	v_lshrrev_b32_e32 v12, 26, v12
	v_add_u32_e32 v12, v11, v12
	v_lshlrev_b32_e32 v10, 3, v5
	v_ashrrev_i32_e32 v13, 6, v12
	v_and_b32_e32 v12, 0xc0, v12
	v_and_b32_e32 v10, -16, v10
	v_lshlrev_b32_e32 v5, 5, v5
	v_sub_u32_e32 v11, v11, v12
	v_add_u32_e32 v10, v13, v10
	v_and_b32_e32 v5, 32, v5
	v_ashrrev_i16_sdwa v11, v14, sext(v11) dst_sel:DWORD dst_unused:UNUSED_PAD src0_sel:DWORD src1_sel:BYTE_0
	v_add_u32_sdwa v12, v5, sext(v11) dst_sel:DWORD dst_unused:UNUSED_PAD src0_sel:DWORD src1_sel:WORD_0
	v_ashrrev_i32_e32 v11, 31, v10
	v_readfirstlane_b32 s1, v153
	v_lshlrev_b64 v[10:11], 11, v[10:11]
	v_ashrrev_i32_e32 v13, 31, v12
	s_mov_b32 m0, s1
	s_lshl_b32 s1, s27, 11
	v_lshl_add_u64 v[14:15], s[8:9], 0, v[10:11]
	v_lshlrev_b64 v[12:13], 1, v[12:13]
	s_waitcnt lgkmcnt(0)
	s_add_u32 s8, s2, s1
	v_lshl_add_u64 v[14:15], v[14:15], 0, v[12:13]
	s_addc_u32 s9, s3, 0
	s_or_b32 s14, s0, 0x80
	global_load_lds_dwordx4 v[14:15], off
	v_lshl_add_u64 v[14:15], s[8:9], 0, v[6:7]
	v_readfirstlane_b32 s1, v150
	s_ashr_i32 s15, s14, 31
	v_lshl_add_u64 v[14:15], v[14:15], 0, v[8:9]
	s_mov_b32 m0, s1
	s_lshl_b64 s[14:15], s[14:15], 11
	global_load_lds_dwordx4 v[14:15], off
	v_lshl_add_u64 v[14:15], s[8:9], 0, v[10:11]
	v_readfirstlane_b32 s1, v152
	s_add_u32 s14, s4, s14
	v_lshl_add_u64 v[14:15], v[14:15], 0, v[12:13]
	s_mov_b32 m0, s1
	s_addc_u32 s15, s5, s15
	global_load_lds_dwordx4 v[14:15], off
	v_lshl_add_u64 v[14:15], s[14:15], 0, v[6:7]
	v_readfirstlane_b32 s1, v154
	v_lshl_add_u64 v[14:15], v[14:15], 0, v[8:9]
	s_mov_b32 m0, s1
	s_add_u32 s8, s8, 0x40000
	global_load_lds_dwordx4 v[14:15], off
	v_lshl_add_u64 v[14:15], s[14:15], 0, v[10:11]
	v_readfirstlane_b32 s1, v155
	s_addc_u32 s9, s9, 0
	v_lshl_add_u64 v[14:15], v[14:15], 0, v[12:13]
	s_mov_b32 m0, s1
	v_lshl_add_u64 v[6:7], s[8:9], 0, v[6:7]
	v_readfirstlane_b32 s1, v156
	global_load_lds_dwordx4 v[14:15], off
	v_lshl_add_u64 v[6:7], v[6:7], 0, v[8:9]
	s_mov_b32 m0, s1
	v_readfirstlane_b32 s1, v157
	global_load_lds_dwordx4 v[6:7], off
	v_lshl_add_u64 v[6:7], s[8:9], 0, v[10:11]
	v_lshl_add_u64 v[6:7], v[6:7], 0, v[12:13]
	s_mov_b32 m0, s1
	s_nop 0
	global_load_lds_dwordx4 v[6:7], off

; #define BAR8 __builtin_amdgcn_s_barrier()
; #define G_XF (outp())
; #define G_SS ((float*)(wsp() + OFF_SS))
;     ...
;     STAGE8(SB8(0, 0), Bt, K, bcol, 0); STAGE8(SA8(0, 0), A, lda, brow, 0);
;     STAGE8(SB8(0, 1), Bt, K, bcol + 128, 0); STAGE8(SA8(0, 1), A, lda, brow + 128, 0);
;   }
;   if (wr == 1) BAR8;
; __global__ void __launch_bounds__(512, 2) mega(Params p) {
;     ...
;     for (int item = bid; item < 4 * 64; item += nb) {
;       const int nt = item >> 6, mt = item & 63;
;       e.ss = nullptr; e.xf = G_XF; e.xb = G_XB; e.ss_out = G_SS;
;       gemm_tile<EPI_RESID, 256, false>(G_ACT, 2816, wb + W_DOWN, 2816, mt * 256, nt * 256, e);
.LBB0_1322:
	s_mov_b32 s0, 24
	s_mov_b32 s0, 25
	s_ashr_i32 s1, s0, 31
	s_lshl_b64 s[0:1], s[0:1], 3
	s_add_u32 s0, s70, s0
	s_addc_u32 s1, s71, s1
	v_readlane_b32 s6, v255, 60
	v_readlane_b32 s7, v255, 61
	s_nop 4
	s_mov_b32 s0, 25
	s_ashr_i32 s1, s0, 31
	s_lshl_b64 s[0:1], s[0:1], 3
	s_add_u32 s0, s70, s0
	s_addc_u32 s1, s71, s1
	s_mov_b32 s2, 25
	v_readlane_b32 s0, v255, 60
	v_readlane_b32 s1, v255, 61
	s_nop 4
	s_ashr_i32 s3, s2, 31
	s_lshl_b64 s[2:3], s[2:3], 3
	s_add_u32 s2, s70, s2
	s_addc_u32 s3, s71, s3
	v_mov_b32_e32 v3, v224
	v_readlane_b32 s2, v255, 60
	v_readlane_b32 s3, v255, 61
	s_nop 4
	s_lshl_b32 s8, s24, 8
	v_bfe_i32 v1, v3, 27, 1
	s_waitcnt vmcnt(10)
	v_lshlrev_b32_e32 v150, 4, v3
	v_lshrrev_b32_e32 v1, 22, v1
	v_add_u32_e32 v1, v150, v1
	v_and_b32_e32 v1, 0xfffffc00, v1
	v_ashrrev_i32_e32 v0, 31, v3
	v_sub_u32_e32 v1, v150, v1
	v_lshrrev_b32_e32 v0, 26, v0
	v_lshrrev_b32_e32 v5, 4, v1
	v_add_u32_e32 v0, v3, v0
	v_bitop3_b32 v6, v5, v1, 32 bitop3:0x6c
	v_ashrrev_i32_e32 v1, 31, v1
	v_ashrrev_i32_e32 v0, 6, v0
	v_lshrrev_b32_e32 v1, 26, v1
	v_lshlrev_b32_e32 v5, 3, v0
	v_add_u32_e32 v1, v6, v1
	v_and_b32_e32 v5, -16, v5
	v_ashrrev_i32_e32 v1, 6, v1
	s_and_b32 s25, s8, 0x3f00
	s_lshl_b32 s8, s24, 2
	v_add_u32_e32 v5, v1, v5
	v_mul_i32_i24_e32 v1, 64, v1
	s_and_b32 s8, s8, 0xffffff00
	v_lshlrev_b32_e32 v0, 5, v0
	v_sub_u32_e32 v1, v6, v1
	v_mov_b32_e32 v15, 1
	s_mul_i32 s12, s8, 0x1600
	v_and_b32_e32 v0, 32, v0
	v_ashrrev_i16_sdwa v1, v15, sext(v1) dst_sel:DWORD dst_unused:UNUSED_PAD src0_sel:DWORD src1_sel:BYTE_0
	s_movk_i32 s27, 0xb00
	s_mul_hi_i32 s9, s8, 0x1600
	s_add_u32 s12, s14, s12
	v_add_u32_sdwa v0, v0, sext(v1) dst_sel:DWORD dst_unused:UNUSED_PAD src0_sel:DWORD src1_sel:WORD_0
	v_mad_i64_i32 v[132:133], s[30:31], v5, s27, 0
	s_addc_u32 s13, s15, s9
	v_lshlrev_b64 v[24:25], 1, v[132:133]
	v_ashrrev_i32_e32 v1, 31, v0
	v_lshl_add_u64 v[8:9], s[12:13], 0, v[24:25]
	v_lshlrev_b64 v[6:7], 1, v[0:1]
	s_waitcnt vmcnt(9)
	v_add_u32_e32 v152, 0x2000, v150
	v_lshl_add_u64 v[10:11], v[8:9], 0, v[6:7]
	v_ashrrev_i32_e32 v8, 31, v152
	v_lshrrev_b32_e32 v8, 22, v8
	v_add_u32_e32 v8, v152, v8
	v_ashrrev_i32_e32 v8, 10, v8
	v_mul_i32_i24_e32 v9, 0x400, v8
	v_sub_u32_e32 v9, v152, v9
	v_lshrrev_b32_e32 v12, 4, v9
	v_bitop3_b32 v9, v12, v9, 32 bitop3:0x6c
	v_ashrrev_i32_e32 v13, 31, v9
	v_add_u32_e32 v151, 0x10000, v150
	v_lshrrev_b32_e32 v13, 26, v13
	v_readfirstlane_b32 s9, v151
	v_lshlrev_b32_e32 v12, 3, v8
	v_add_u32_e32 v13, v9, v13
	s_waitcnt vmcnt(8)
	v_add_u32_e32 v157, 0x12000, v150
	v_mov_b32_e32 v4, v2
	s_mov_b32 m0, s9
	v_and_b32_e32 v12, -16, v12
	v_ashrrev_i32_e32 v14, 6, v13
	v_readfirstlane_b32 s9, v157
	global_load_lds_dwordx4 v[10:11], off
	v_add_u32_e32 v22, v14, v12
	v_and_b32_e32 v12, 0xc0, v13
	s_mov_b32 m0, s9
	s_mul_i32 s9, s25, 0xb00
	v_lshlrev_b32_e32 v8, 5, v8
	v_sub_u32_e32 v9, v9, v12
	v_mad_i64_i32 v[136:137], s[30:31], v22, s27, 0
	s_lshl_b32 s27, s9, 1
	v_and_b32_e32 v8, 32, v8
	v_ashrrev_i16_sdwa v9, v15, sext(v9) dst_sel:DWORD dst_unused:UNUSED_PAD src0_sel:DWORD src1_sel:BYTE_0
	s_waitcnt lgkmcnt(0)
	s_add_u32 s9, s2, s27
	v_add_u32_sdwa v134, v8, sext(v9) dst_sel:DWORD dst_unused:UNUSED_PAD src0_sel:DWORD src1_sel:WORD_0
	v_lshlrev_b64 v[26:27], 1, v[136:137]
	s_addc_u32 s29, s3, 0
	v_lshl_add_u64 v[12:13], s[12:13], 0, v[26:27]
	v_ashrrev_i32_e32 v135, 31, v134
	s_add_u32 s12, s9, 0x2000000
	v_lshlrev_b64 v[8:9], 1, v[134:135]
	s_addc_u32 s13, s29, 0
	v_lshl_add_u64 v[12:13], v[12:13], 0, v[8:9]
	v_lshl_add_u64 v[14:15], s[12:13], 0, v[24:25]
	v_readfirstlane_b32 s30, v150
	global_load_lds_dwordx4 v[12:13], off
	v_lshl_add_u64 v[14:15], v[14:15], 0, v[6:7]
	s_mov_b32 m0, s30
	v_lshl_add_u64 v[16:17], s[12:13], 0, v[26:27]
	v_readfirstlane_b32 s12, v152
	s_or_b32 s30, s8, 0x80
	global_load_lds_dwordx4 v[14:15], off
	s_mov_b32 m0, s12
	s_mul_i32 s12, s30, 0x1600
	s_mul_hi_i32 s13, s30, 0x1600
	s_add_u32 s12, s14, s12
	s_addc_u32 s13, s15, s13
	v_add_u32_e32 v160, 0x14000, v150
	v_lshl_add_u64 v[16:17], v[16:17], 0, v[8:9]
	v_lshl_add_u64 v[18:19], s[12:13], 0, v[24:25]
	v_readfirstlane_b32 s31, v160
	v_add_u32_e32 v161, 0x16000, v150
	global_load_lds_dwordx4 v[16:17], off
	v_lshl_add_u64 v[18:19], v[18:19], 0, v[6:7]
	s_mov_b32 m0, s31
	v_lshl_add_u64 v[20:21], s[12:13], 0, v[26:27]
	v_readfirstlane_b32 s12, v161
	global_load_lds_dwordx4 v[18:19], off
	s_mov_b32 m0, s12
	s_add_u32 s12, s9, 0x20b0000
	s_addc_u32 s13, s29, 0
	v_add_u32_e32 v162, 0x4000, v150
	v_lshl_add_u64 v[20:21], v[20:21], 0, v[8:9]
	v_lshl_add_u64 v[24:25], s[12:13], 0, v[24:25]
	v_readfirstlane_b32 s9, v162
	global_load_lds_dwordx4 v[20:21], off
	v_lshl_add_u64 v[24:25], v[24:25], 0, v[6:7]
	s_mov_b32 m0, s9
	v_add_u32_e32 v163, 0x6000, v150
	global_load_lds_dwordx4 v[24:25], off
	v_lshl_add_u64 v[24:25], s[12:13], 0, v[26:27]
	v_readfirstlane_b32 s9, v163
	v_lshl_add_u64 v[24:25], v[24:25], 0, v[8:9]
	s_mov_b32 m0, s9
	v_ashrrev_i32_e32 v23, 8, v3
	global_load_lds_dwordx4 v[24:25], off
	v_cmp_eq_u32_e32 vcc, 1, v23
	s_and_saveexec_b64 s[12:13], vcc
	s_cbranch_execz .LBB0_1324
	s_barrier

; DI float h_lo(unsigned u) { return (float)__builtin_bit_cast(h2_t, u)[0]; }
; DI float h_hi(unsigned u) { return (float)__builtin_bit_cast(h2_t, u)[1]; }
; DI int tid_opaque() { int t = threadIdx.x; asm volatile("" : "+v"(t)); return t; }
; #define G_XF (outp())
; __global__ void __launch_bounds__(512, 2) mega(Params p) {
;     ...
;   {
;     const int t2 = tid_opaque();
;     const int w = t2 >> 6, l = t2 & 63;
;     const float4* gf = (const float4*)inp(23);
;     for (int row = bid * 8 + w; row < NTOK; row += nb * 8) {
;       const uint2* xp = (const uint2*)(G_XB + (size_t)row * DM);
;       float4* op = (float4*)(G_XF + (size_t)row * DM);
;       float4 v[4];
;       float s2 = 0.f;
; #pragma unroll
;       for (int i = 0; i < 4; ++i) {
;         const uint2 u = xp[l + 64 * i];
;         v[i].x = h_lo(u.x); v[i].y = h_hi(u.x);
;         v[i].z = h_lo(u.y); v[i].w = h_hi(u.y);
;         s2 += v[i].x * v[i].x + v[i].y * v[i].y + v[i].z * v[i].z + v[i].w * v[i].w;
;       }
; #pragma unroll
;       for (int o = 32; o; o >>= 1) s2 += __shfl_xor(s2, o);
;       const float rr = rsqrtf(s2 * (1.f / 1024.f) + EPS);
; #pragma unroll
;       for (int i = 0; i < 4; ++i) {
;         const float4 g = gf[l + 64 * i];
;         float4 o4 = {v[i].x * rr * g.x, v[i].y * rr * g.y, v[i].z * rr * g.z, v[i].w * rr * g.w};
;         op[l + 64 * i] = o4;
;       }
;     }
.LBB0_1415:
	s_mov_b32 s10, 25
	s_ashr_i32 s11, s10, 31
	s_lshl_b64 s[10:11], s[10:11], 3
	s_add_u32 s10, s70, s10
	s_addc_u32 s11, s71, s11
	v_readlane_b32 s10, v255, 60
	v_readlane_b32 s11, v255, 61
	s_nop 4
	s_mov_b32 s12, 24
	v_cmp_lt_i32_e32 vcc, v8, v1
	s_ashr_i32 s13, s12, 31
	s_waitcnt lgkmcnt(0)
	v_lshl_add_u64 v[16:17], s[10:11], 0, v[4:5]
	global_load_dwordx2 v[20:21], v[16:17], off offset:-1540
	global_load_dwordx2 v[22:23], v[16:17], off offset:-1028
	global_load_dwordx2 v[24:25], v[16:17], off offset:-516
	global_load_dwordx2 v[26:27], v[16:17], off offset:-4
	v_cndmask_b32_e32 v15, v225, v8, vcc
	v_cmp_lt_i32_e32 vcc, v9, v1
	v_lshlrev_b32_e32 v15, 2, v15
	s_lshl_b64 s[10:11], s[12:13], 3
	v_cndmask_b32_e32 v16, v225, v9, vcc
	v_cmp_lt_i32_e32 vcc, v10, v1
	v_lshlrev_b32_e32 v54, 2, v16
	s_add_u32 s10, s70, s10
	v_cndmask_b32_e32 v17, v225, v10, vcc
	v_cmp_lt_i32_e32 vcc, v11, v1
	v_lshlrev_b32_e32 v55, 2, v17
	s_addc_u32 s11, s71, s11
	v_cndmask_b32_e32 v18, v225, v11, vcc
	v_cmp_lt_i32_e32 vcc, v12, v1
	v_lshlrev_b32_e32 v56, 2, v18
	s_load_dwordx2 s[10:11], s[10:11], 0x0
	v_cndmask_b32_e32 v19, v225, v12, vcc
	v_lshlrev_b32_e32 v57, 2, v19
	v_cmp_lt_i32_e32 vcc, v13, v1
	v_add_u32_e32 v0, s0, v0
	v_lshl_add_u64 v[4:5], v[4:5], 0, s[2:3]
	v_cndmask_b32_e32 v28, v225, v13, vcc
	v_lshlrev_b32_e32 v58, 2, v28
	s_waitcnt lgkmcnt(0)
	v_lshl_add_u64 v[28:29], s[10:11], 0, v[6:7]
	v_lshl_add_u64 v[6:7], v[6:7], 0, s[4:5]
	s_waitcnt vmcnt(3)
	v_cvt_f32_f16_sdwa v31, v20 dst_sel:DWORD dst_unused:UNUSED_PAD src0_sel:WORD_1
	s_waitcnt vmcnt(2)
	v_cvt_f32_f16_sdwa v33, v22 dst_sel:DWORD dst_unused:UNUSED_PAD src0_sel:WORD_1
	v_cvt_f32_f16_e32 v30, v20
	v_cvt_f32_f16_e32 v32, v22
	s_waitcnt vmcnt(1)
	v_cvt_f32_f16_sdwa v35, v24 dst_sel:DWORD dst_unused:UNUSED_PAD src0_sel:WORD_1
	s_waitcnt vmcnt(0)
	v_cvt_f32_f16_sdwa v37, v26 dst_sel:DWORD dst_unused:UNUSED_PAD src0_sel:WORD_1
	v_cvt_f32_f16_e32 v20, v21
	v_cvt_f32_f16_e32 v22, v23
	v_cvt_f32_f16_e32 v34, v24
	v_cvt_f32_f16_e32 v36, v26
	v_cvt_f32_f16_sdwa v21, v21 dst_sel:DWORD dst_unused:UNUSED_PAD src0_sel:WORD_1
	v_cvt_f32_f16_sdwa v23, v23 dst_sel:DWORD dst_unused:UNUSED_PAD src0_sel:WORD_1
	v_cvt_f32_f16_e32 v24, v25
	v_cvt_f32_f16_e32 v26, v27
	v_cvt_f32_f16_sdwa v25, v25 dst_sel:DWORD dst_unused:UNUSED_PAD src0_sel:WORD_1
	v_cvt_f32_f16_sdwa v27, v27 dst_sel:DWORD dst_unused:UNUSED_PAD src0_sel:WORD_1
	v_mov_b32_e32 v40, v31
	v_mov_b32_e32 v41, v33
	v_mov_b32_e32 v38, v30
	v_mov_b32_e32 v39, v32
	v_mov_b32_e32 v48, v35
	v_mov_b32_e32 v49, v37
	v_pk_mul_f32 v[40:41], v[40:41], v[40:41]
	v_mov_b32_e32 v42, v20
	v_mov_b32_e32 v43, v22
	v_mov_b32_e32 v46, v34
	v_mov_b32_e32 v47, v36
	v_pk_mul_f32 v[48:49], v[48:49], v[48:49]
	v_pk_fma_f32 v[38:39], v[38:39], v[38:39], v[40:41]
	v_mov_b32_e32 v44, v21
	v_mov_b32_e32 v45, v23
	v_mov_b32_e32 v50, v24
	v_mov_b32_e32 v51, v26
	v_pk_fma_f32 v[40:41], v[46:47], v[46:47], v[48:49]
	v_pk_fma_f32 v[38:39], v[42:43], v[42:43], v[38:39]
	v_mov_b32_e32 v52, v25
	v_mov_b32_e32 v53, v27
	v_pk_fma_f32 v[40:41], v[50:51], v[50:51], v[40:41]
	v_pk_fma_f32 v[38:39], v[44:45], v[44:45], v[38:39]
	v_pk_fma_f32 v[40:41], v[52:53], v[52:53], v[40:41]
	v_add_f32_e32 v38, v38, v39
	v_add_f32_e32 v38, v38, v40
	v_add_f32_e32 v38, v38, v41
	ds_bpermute_b32 v15, v15, v38
	s_waitcnt lgkmcnt(0)
	v_add_f32_e32 v15, v38, v15
	ds_bpermute_b32 v38, v54, v15
	s_waitcnt lgkmcnt(0)
	v_add_f32_e32 v15, v15, v38
	ds_bpermute_b32 v38, v55, v15
	s_waitcnt lgkmcnt(0)
	v_add_f32_e32 v15, v15, v38
	ds_bpermute_b32 v38, v56, v15
	s_waitcnt lgkmcnt(0)
	v_add_f32_e32 v15, v15, v38
	ds_bpermute_b32 v38, v57, v15
	s_waitcnt lgkmcnt(0)
	v_add_f32_e32 v15, v15, v38
	ds_bpermute_b32 v38, v58, v15
	s_waitcnt lgkmcnt(0)
	v_add_f32_e32 v15, v15, v38
	v_fmamk_f32 v15, v15, 0x3a800000, v14
	v_mul_f32_e32 v38, 0x4b800000, v15
	v_cmp_gt_f32_e32 vcc, s1, v15
	s_nop 1
	v_cndmask_b32_e32 v15, v15, v38, vcc
	v_rsq_f32_e32 v15, v15
	s_nop 0
	v_mul_f32_e32 v38, 0x45800000, v15
	v_cndmask_b32_e32 v38, v15, v38, vcc
	v_pk_mul_f32 v[30:31], v[38:39], v[30:31] op_sel_hi:[0,1]
	v_pk_mul_f32 v[20:21], v[38:39], v[20:21] op_sel_hi:[0,1]
	v_pk_mul_f32 v[16:17], v[60:61], v[30:31]
	v_pk_mul_f32 v[18:19], v[62:63], v[20:21]
	global_store_dwordx4 v[28:29], v[16:19], off offset:-3080
	v_pk_mul_f32 v[20:21], v[38:39], v[32:33] op_sel_hi:[0,1]
	v_pk_mul_f32 v[22:23], v[38:39], v[22:23] op_sel_hi:[0,1]
	v_cmp_lt_i32_e32 vcc, s8, v0
	s_or_b64 s[6:7], vcc, s[6:7]
	v_pk_mul_f32 v[76:77], v[64:65], v[20:21]
	v_pk_mul_f32 v[78:79], v[66:67], v[22:23]
	global_store_dwordx4 v[28:29], v[76:79], off offset:-2056
	v_pk_mul_f32 v[20:21], v[38:39], v[34:35] op_sel_hi:[0,1]
	v_pk_mul_f32 v[22:23], v[38:39], v[24:25] op_sel_hi:[0,1]
	v_pk_mul_f32 v[80:81], v[68:69], v[20:21]
	v_pk_mul_f32 v[82:83], v[70:71], v[22:23]
	global_store_dwordx4 v[28:29], v[80:83], off offset:-1032
	v_pk_mul_f32 v[20:21], v[38:39], v[36:37] op_sel_hi:[0,1]
	v_pk_mul_f32 v[22:23], v[38:39], v[26:27] op_sel_hi:[0,1]
	v_pk_mul_f32 v[84:85], v[72:73], v[20:21]
	v_pk_mul_f32 v[86:87], v[74:75], v[22:23]
	global_store_dwordx4 v[28:29], v[84:87], off offset:-8
	s_andn2_b64 exec, exec, s[6:7]
	s_cbranch_execnz .LBB0_1415
